# 2-phase K-loop: LDS-DMA stages issued before the ds_reads in each load segment
# speedup vs baseline: 1.0166x; 1.0050x over previous
; #define PG8_STAGE(bufoff, gbase, voff) do { _Pragma("unroll") for (int _i = 0; _i < 2; ++_i) \
;         __builtin_amdgcn_global_load_lds((const unsigned*)((const char*)(gbase) + (voff)[_i]), (LAS unsigned*)(lds + (bufoff) + ldsw + _i * 8192), 16, 0, 0); } while (0)
; #define PG8_LDA(dst, b, h) do { _Pragma("unroll") for (int m = 0; m < 4; ++m) _Pragma("unroll") for (int k = 0; k < 2; ++k) dst[m][k] = *(const LAS bf16x8*)(lds + PG8_SA(b, h) + aoff + m * 2048 + k * 1024); } while (0)
; #define PG8_LDB(dst, b, h) do { _Pragma("unroll") for (int n = 0; n < 2; ++n) _Pragma("unroll") for (int k = 0; k < 2; ++k) dst[n][k] = *(const LAS bf16x8*)(lds + PG8_SB(b, h) + boff + n * 2048 + k * 1024); } while (0)
; #define PG8_MMA(ai, bj, At, Bt) do { __builtin_amdgcn_s_setprio(1); _Pragma("unroll") for (int m = 0; m < 4; ++m) _Pragma("unroll") for (int n = 0; n < 2; ++n) _Pragma("unroll") for (int k = 0; k < 2; ++k) \
;         acc[ai][bj][m][n] = __builtin_amdgcn_mfma_f32_16x16x32_bf16(Bt[n][k], At[m][k], acc[ai][bj][m][n], 0, 0, 0); __builtin_amdgcn_s_setprio(0); } while (0)
; template <class Epi>
; __device__ __forceinline__ void gemm_phase(LAS unsigned char* lds, const Gemm g, const StaticOrder& S, const Epi& E) {
;     ...
;         const char* nA = has_next ? (const char*)g.A + (size_t)nxt.pm * tstepA : cA; const char* nB = has_next ? (const char*)g.Bt + (size_t)nxt.pn * tstepB : cB;
;         for (int t = 0; t < nt; t += 2) {
;             const bool last = (t == nt - 2);
;             const char* a1 = cA + (size_t)(t + 1) * kstep;
;             const char* a2 = last ? nA : cA + (size_t)(t + 2) * kstep; const char* b2 = last ? nB : cB + (size_t)(t + 2) * kstep;
;             const char* a3 = a2 + kstep; const char* b3 = b2 + kstep;
;             PG8_LDB(B0, 0, 0); PG8_SCHED; PG8_LDA(At, 0, 0); PG8_STAGE(PG8_SA(1, 1), a1 + hstepA, voffA);
;             PG8_WAIT_L(8); PG8_BAR; PG8_WAIT_L(0); PG8_MMA(0, 0, At, B0); PG8_BAR; PG8_SCHED;
;             PG8_LDB(B1, 0, 1); PG8_STAGE(PG8_SB(0, 0), b2, voffB);
;             PG8_BAR; PG8_WAIT_L(0); PG8_MMA(0, 1, At, B1); PG8_BAR;
;             PG8_LDA(At, 0, 1); PG8_STAGE(PG8_SA(0, 0), a2, voffA);
;             PG8_BAR; PG8_WAIT_L(0); PG8_MMA(1, 0, At, B0); PG8_BAR; PG8_SCHED;
;             PG8_STAGE(PG8_SB(0, 1), b2 + hstepB, voffB);
;             PG8_WAIT_V(6); PG8_BAR; PG8_MMA(1, 1, At, B1); PG8_BAR;
.LBB0_140:
	v_mov_b64_e32 v[0:1], 0x800
	s_ashr_i32 s15, s14, 31
	v_cmp_lt_i64_e32 vcc, s[16:17], v[0:1]
	s_lshl_b64 s[16:17], s[14:15], 20
	v_readlane_b32 s18, v252, 53
	v_readlane_b32 s19, v252, 54
	s_add_u32 s16, s18, s16
	s_addc_u32 s17, s19, s17
	s_and_b64 s[18:19], vcc, exec
	s_cselect_b32 s15, s17, s23
	s_cselect_b32 s49, s16, s22
	s_ashr_i32 s5, s4, 31
	s_lshl_b64 s[18:19], s[4:5], 20
	s_add_u32 s18, s34, s18
	s_addc_u32 s19, s35, s19
	s_and_b64 s[26:27], vcc, exec
	s_cselect_b32 s5, s19, s25
	s_cselect_b32 s50, s18, s24
	s_add_u32 s22, s22, 0x84000
	s_addc_u32 s23, s23, 0
	s_add_u32 s51, s24, 0x8000
	s_addc_u32 s52, s25, 0
	s_mov_b32 s54, -2
	s_add_u32 s24, s22, 0xfff84000
	s_addc_u32 s25, s23, -1
	s_cmp_eq_u32 s54, 28
	s_cselect_b32 s28, s49, s24
	s_cselect_b32 s29, s15, s25
	s_cselect_b32 s24, s50, s51
	s_cselect_b32 s25, s5, s52
	s_add_u32 s26, s28, 0x4000
	s_addc_u32 s27, s29, 0
	s_add_i32 m0, s37, 0xc000
	v_lshl_add_u64 v[188:189], s[22:23], 0, v[128:129]
	global_load_lds_dwordx4 v[188:189], off
	s_add_i32 m0, s37, 0xe000
	v_lshl_add_u64 v[188:189], s[22:23], 0, v[130:131]
	global_load_lds_dwordx4 v[188:189], off
	s_mov_b32 s55, 0x10000
	v_add_u32_e32 v148, s55, v134
	ds_read_b128 v[136:139], v148
	ds_read_b128 v[144:147], v148 offset:2048
	ds_read_b128 v[140:143], v148 offset:1024
	ds_read_b128 v[148:151], v148 offset:3072
	ds_read_b128 v[156:159], v135
	ds_read_b128 v[164:167], v135 offset:2048
	ds_read_b128 v[172:175], v135 offset:4096
	ds_read_b128 v[180:183], v135 offset:6144
	ds_read_b128 v[160:163], v135 offset:1024
	ds_read_b128 v[168:171], v135 offset:3072
	ds_read_b128 v[176:179], v135 offset:5120
	ds_read_b128 v[184:187], v135 offset:7168
	s_mov_b32 s58, 0x14000
	s_add_i32 s55, s55, s36
	v_add_u32_e32 v152, s58, v134
	ds_read_b128 v[188:191], v152
	ds_read_b128 v[196:199], v152 offset:2048
	ds_read_b128 v[192:195], v152 offset:1024
	ds_read_b128 v[200:203], v152 offset:3072
	s_waitcnt lgkmcnt(0)
	s_barrier
	v_mfma_f32_16x16x32_bf16 v[124:127], v[136:139], v[156:159], 0
	s_setprio 1
	v_mfma_f32_16x16x32_bf16 v[120:123], v[144:147], v[156:159], 0
	v_mfma_f32_16x16x32_bf16 v[108:111], v[136:139], v[164:167], 0
	v_mfma_f32_16x16x32_bf16 v[104:107], v[144:147], v[164:167], 0
	v_mfma_f32_16x16x32_bf16 v[92:95], v[136:139], v[172:175], 0
	v_mfma_f32_16x16x32_bf16 v[88:91], v[144:147], v[172:175], 0
	v_mfma_f32_16x16x32_bf16 v[76:79], v[136:139], v[180:183], 0
	v_mfma_f32_16x16x32_bf16 v[72:75], v[144:147], v[180:183], 0
	v_mfma_f32_16x16x32_bf16 v[124:127], v[140:143], v[160:163], v[124:127]
	v_mfma_f32_16x16x32_bf16 v[120:123], v[148:151], v[160:163], v[120:123]
	v_mfma_f32_16x16x32_bf16 v[108:111], v[140:143], v[168:171], v[108:111]
	v_mfma_f32_16x16x32_bf16 v[104:107], v[148:151], v[168:171], v[104:107]
	v_mfma_f32_16x16x32_bf16 v[92:95], v[140:143], v[176:179], v[92:95]
	v_mfma_f32_16x16x32_bf16 v[88:91], v[148:151], v[176:179], v[88:91]
	v_mfma_f32_16x16x32_bf16 v[76:79], v[140:143], v[184:187], v[76:79]
	v_mfma_f32_16x16x32_bf16 v[72:75], v[148:151], v[184:187], v[72:75]
	v_mfma_f32_16x16x32_bf16 v[116:119], v[188:191], v[156:159], 0
	v_mfma_f32_16x16x32_bf16 v[112:115], v[196:199], v[156:159], 0
	v_mfma_f32_16x16x32_bf16 v[100:103], v[188:191], v[164:167], 0
	v_mfma_f32_16x16x32_bf16 v[96:99], v[196:199], v[164:167], 0
	v_mfma_f32_16x16x32_bf16 v[84:87], v[188:191], v[172:175], 0
	v_mfma_f32_16x16x32_bf16 v[80:83], v[196:199], v[172:175], 0
	v_mfma_f32_16x16x32_bf16 v[68:71], v[188:191], v[180:183], 0
	v_mfma_f32_16x16x32_bf16 v[64:67], v[196:199], v[180:183], 0
	v_mfma_f32_16x16x32_bf16 v[116:119], v[192:195], v[160:163], v[116:119]
	v_mfma_f32_16x16x32_bf16 v[112:115], v[200:203], v[160:163], v[112:115]
	v_mfma_f32_16x16x32_bf16 v[100:103], v[192:195], v[168:171], v[100:103]
	v_mfma_f32_16x16x32_bf16 v[96:99], v[200:203], v[168:171], v[96:99]
	v_mfma_f32_16x16x32_bf16 v[84:87], v[192:195], v[176:179], v[84:87]
	v_mfma_f32_16x16x32_bf16 v[80:83], v[200:203], v[176:179], v[80:83]
	v_mfma_f32_16x16x32_bf16 v[68:71], v[192:195], v[184:187], v[68:71]
	s_setprio 0
	v_mfma_f32_16x16x32_bf16 v[64:67], v[200:203], v[184:187], v[64:67]
	s_barrier
	s_mov_b32 m0, s55
	v_lshl_add_u64 v[204:205], s[24:25], 0, v[128:129]
	global_load_lds_dwordx4 v[204:205], off
	s_add_i32 m0, s55, 0x2000
	v_lshl_add_u64 v[204:205], s[24:25], 0, v[130:131]
	global_load_lds_dwordx4 v[204:205], off
	s_mov_b32 m0, s37
	v_lshl_add_u64 v[204:205], s[28:29], 0, v[128:129]
	global_load_lds_dwordx4 v[204:205], off
	s_mov_b32 m0, s38
	v_lshl_add_u64 v[204:205], s[28:29], 0, v[130:131]
	global_load_lds_dwordx4 v[204:205], off
	s_add_u32 s56, s24, 0x80000
	s_addc_u32 s57, s25, 0
	s_add_i32 s55, s58, s36
	s_mov_b32 m0, s55
	v_lshl_add_u64 v[204:205], s[56:57], 0, v[128:129]
	global_load_lds_dwordx4 v[204:205], off
	s_add_i32 m0, s55, 0x2000
	v_lshl_add_u64 v[204:205], s[56:57], 0, v[130:131]
	global_load_lds_dwordx4 v[204:205], off
	ds_read_b128 v[156:159], v135 offset:16384
	ds_read_b128 v[164:167], v135 offset:18432
	ds_read_b128 v[172:175], v135 offset:20480
	ds_read_b128 v[180:183], v135 offset:22528
	ds_read_b128 v[160:163], v135 offset:17408
	ds_read_b128 v[168:171], v135 offset:19456
	ds_read_b128 v[176:179], v135 offset:21504
	ds_read_b128 v[184:187], v135 offset:23552
	s_waitcnt vmcnt(6)
	s_waitcnt lgkmcnt(0)
	s_barrier
; #define PG8_STAGE(bufoff, gbase, voff) do { _Pragma("unroll") for (int _i = 0; _i < 2; ++_i) \
;         __builtin_amdgcn_global_load_lds((const unsigned*)((const char*)(gbase) + (voff)[_i]), (LAS unsigned*)(lds + (bufoff) + ldsw + _i * 8192), 16, 0, 0); } while (0)
; #define PG8_LDA(dst, b, h) do { _Pragma("unroll") for (int m = 0; m < 4; ++m) _Pragma("unroll") for (int k = 0; k < 2; ++k) dst[m][k] = *(const LAS bf16x8*)(lds + PG8_SA(b, h) + aoff + m * 2048 + k * 1024); } while (0)
; #define PG8_LDB(dst, b, h) do { _Pragma("unroll") for (int n = 0; n < 2; ++n) _Pragma("unroll") for (int k = 0; k < 2; ++k) dst[n][k] = *(const LAS bf16x8*)(lds + PG8_SB(b, h) + boff + n * 2048 + k * 1024); } while (0)
; #define PG8_MMA(ai, bj, At, Bt) do { __builtin_amdgcn_s_setprio(1); _Pragma("unroll") for (int m = 0; m < 4; ++m) _Pragma("unroll") for (int n = 0; n < 2; ++n) _Pragma("unroll") for (int k = 0; k < 2; ++k) \
;         acc[ai][bj][m][n] = __builtin_amdgcn_mfma_f32_16x16x32_bf16(Bt[n][k], At[m][k], acc[ai][bj][m][n], 0, 0, 0); __builtin_amdgcn_s_setprio(0); } while (0)
; #define PG8_WAIT_V(n) asm volatile("s_waitcnt vmcnt(" #n ")" ::: "memory")
; #define PG8_WAIT_L(n) asm volatile("s_waitcnt lgkmcnt(" #n ")" ::: "memory")
; #define PG8_BAR __builtin_amdgcn_s_barrier()
; #define PG8_SCHED __builtin_amdgcn_sched_barrier(0)
; template <class Epi>
; __device__ __forceinline__ void gemm_phase(LAS unsigned char* lds, const Gemm g, const StaticOrder& S, const Epi& E) {
;     ...
;             PG8_BAR; PG8_WAIT_L(0); PG8_MMA(1, 0, At, B0); PG8_BAR; PG8_SCHED;
;             PG8_STAGE(PG8_SB(0, 1), b2 + hstepB, voffB);
;             PG8_WAIT_V(6); PG8_BAR; PG8_MMA(1, 1, At, B1); PG8_BAR;
;             PG8_LDB(B0, 1, 0); PG8_SCHED; PG8_LDA(At, 1, 0); PG8_STAGE(PG8_SA(0, 1), a2 + hstepA, voffA);
;             PG8_WAIT_L(8); PG8_BAR; PG8_WAIT_L(0); PG8_MMA(0, 0, At, B0); PG8_BAR; PG8_SCHED;
;             PG8_LDB(B1, 1, 1); PG8_STAGE(PG8_SB(1, 0), b3, voffB);
;             PG8_BAR; PG8_WAIT_L(0); PG8_MMA(0, 1, At, B1); PG8_BAR;
	v_mfma_f32_16x16x32_bf16 v[60:63], v[136:139], v[156:159], 0
	s_setprio 1
	v_mfma_f32_16x16x32_bf16 v[56:59], v[144:147], v[156:159], 0
	v_mfma_f32_16x16x32_bf16 v[44:47], v[136:139], v[164:167], 0
	v_mfma_f32_16x16x32_bf16 v[40:43], v[144:147], v[164:167], 0
	v_mfma_f32_16x16x32_bf16 v[28:31], v[136:139], v[172:175], 0
	v_mfma_f32_16x16x32_bf16 v[24:27], v[144:147], v[172:175], 0
	v_mfma_f32_16x16x32_bf16 v[12:15], v[136:139], v[180:183], 0
	v_mfma_f32_16x16x32_bf16 v[8:11], v[144:147], v[180:183], 0
	v_mfma_f32_16x16x32_bf16 v[60:63], v[140:143], v[160:163], v[60:63]
	v_mfma_f32_16x16x32_bf16 v[56:59], v[148:151], v[160:163], v[56:59]
	v_mfma_f32_16x16x32_bf16 v[44:47], v[140:143], v[168:171], v[44:47]
	v_mfma_f32_16x16x32_bf16 v[40:43], v[148:151], v[168:171], v[40:43]
	v_mfma_f32_16x16x32_bf16 v[28:31], v[140:143], v[176:179], v[28:31]
	v_mfma_f32_16x16x32_bf16 v[24:27], v[148:151], v[176:179], v[24:27]
	v_mfma_f32_16x16x32_bf16 v[12:15], v[140:143], v[184:187], v[12:15]
	v_mfma_f32_16x16x32_bf16 v[8:11], v[148:151], v[184:187], v[8:11]
	v_mfma_f32_16x16x32_bf16 v[52:55], v[188:191], v[156:159], 0
	v_mfma_f32_16x16x32_bf16 v[48:51], v[196:199], v[156:159], 0
	s_add_i32 s55, 0, 0x18000
	v_add_u32_e32 v148, s55, v134
	v_mfma_f32_16x16x32_bf16 v[36:39], v[188:191], v[164:167], 0
	v_mfma_f32_16x16x32_bf16 v[32:35], v[196:199], v[164:167], 0
	v_mfma_f32_16x16x32_bf16 v[20:23], v[188:191], v[172:175], 0
	v_mfma_f32_16x16x32_bf16 v[16:19], v[196:199], v[172:175], 0
	v_mfma_f32_16x16x32_bf16 v[4:7], v[188:191], v[180:183], 0
	v_mfma_f32_16x16x32_bf16 v[0:3], v[196:199], v[180:183], 0
	v_mfma_f32_16x16x32_bf16 v[52:55], v[192:195], v[160:163], v[52:55]
	v_mfma_f32_16x16x32_bf16 v[48:51], v[200:203], v[160:163], v[48:51]
	v_mfma_f32_16x16x32_bf16 v[36:39], v[192:195], v[168:171], v[36:39]
	v_mfma_f32_16x16x32_bf16 v[32:35], v[200:203], v[168:171], v[32:35]
	v_mfma_f32_16x16x32_bf16 v[20:23], v[192:195], v[176:179], v[20:23]
	v_mfma_f32_16x16x32_bf16 v[16:19], v[200:203], v[176:179], v[16:19]
	v_mfma_f32_16x16x32_bf16 v[4:7], v[192:195], v[184:187], v[4:7]
	s_setprio 0
	v_mfma_f32_16x16x32_bf16 v[0:3], v[200:203], v[184:187], v[0:3]
	s_barrier
	s_add_u32 s28, s28, 0x80000
	s_addc_u32 s29, s29, 0
	s_mov_b32 m0, s39
	v_lshl_add_u64 v[188:189], s[28:29], 0, v[128:129]
	global_load_lds_dwordx4 v[188:189], off
	s_mov_b32 m0, s40
	v_lshl_add_u64 v[188:189], s[28:29], 0, v[130:131]
	global_load_lds_dwordx4 v[188:189], off
	ds_read_b128 v[136:139], v148
	ds_read_b128 v[144:147], v148 offset:2048
	ds_read_b128 v[140:143], v148 offset:1024
	ds_read_b128 v[148:151], v148 offset:3072
	ds_read_b128 v[156:159], v135 offset:32768
	ds_read_b128 v[164:167], v135 offset:34816
	ds_read_b128 v[172:175], v135 offset:36864
	ds_read_b128 v[180:183], v135 offset:38912
	ds_read_b128 v[160:163], v135 offset:33792
	ds_read_b128 v[168:171], v135 offset:35840
	ds_read_b128 v[176:179], v135 offset:37888
	ds_read_b128 v[184:187], v135 offset:39936
	s_mov_b32 s56, 0x1c000
	s_add_u32 s28, s24, 0x4000
	s_addc_u32 s29, s25, 0
	s_add_i32 s55, s55, s36
	v_add_u32_e32 v152, s56, v134
	ds_read_b128 v[188:191], v152
	ds_read_b128 v[196:199], v152 offset:2048
	ds_read_b128 v[192:195], v152 offset:1024
	ds_read_b128 v[200:203], v152 offset:3072
	s_waitcnt lgkmcnt(0)
	s_barrier
	v_mfma_f32_16x16x32_bf16 v[124:127], v[136:139], v[156:159], v[124:127]
	s_setprio 1
	v_mfma_f32_16x16x32_bf16 v[120:123], v[144:147], v[156:159], v[120:123]
	v_mfma_f32_16x16x32_bf16 v[108:111], v[136:139], v[164:167], v[108:111]
	v_mfma_f32_16x16x32_bf16 v[104:107], v[144:147], v[164:167], v[104:107]
	v_mfma_f32_16x16x32_bf16 v[92:95], v[136:139], v[172:175], v[92:95]
	v_mfma_f32_16x16x32_bf16 v[88:91], v[144:147], v[172:175], v[88:91]
	v_mfma_f32_16x16x32_bf16 v[76:79], v[136:139], v[180:183], v[76:79]
	v_mfma_f32_16x16x32_bf16 v[72:75], v[144:147], v[180:183], v[72:75]
	v_mfma_f32_16x16x32_bf16 v[124:127], v[140:143], v[160:163], v[124:127]
	v_mfma_f32_16x16x32_bf16 v[120:123], v[148:151], v[160:163], v[120:123]
	v_mfma_f32_16x16x32_bf16 v[108:111], v[140:143], v[168:171], v[108:111]
	v_mfma_f32_16x16x32_bf16 v[104:107], v[148:151], v[168:171], v[104:107]
	v_mfma_f32_16x16x32_bf16 v[92:95], v[140:143], v[176:179], v[92:95]
	v_mfma_f32_16x16x32_bf16 v[88:91], v[148:151], v[176:179], v[88:91]
	v_mfma_f32_16x16x32_bf16 v[76:79], v[140:143], v[184:187], v[76:79]
	v_mfma_f32_16x16x32_bf16 v[72:75], v[148:151], v[184:187], v[72:75]
	v_mfma_f32_16x16x32_bf16 v[116:119], v[188:191], v[156:159], v[116:119]
	v_mfma_f32_16x16x32_bf16 v[112:115], v[196:199], v[156:159], v[112:115]
	v_mfma_f32_16x16x32_bf16 v[100:103], v[188:191], v[164:167], v[100:103]
	v_mfma_f32_16x16x32_bf16 v[96:99], v[196:199], v[164:167], v[96:99]
	v_mfma_f32_16x16x32_bf16 v[84:87], v[188:191], v[172:175], v[84:87]
	v_mfma_f32_16x16x32_bf16 v[80:83], v[196:199], v[172:175], v[80:83]
	v_mfma_f32_16x16x32_bf16 v[68:71], v[188:191], v[180:183], v[68:71]
	v_mfma_f32_16x16x32_bf16 v[64:67], v[196:199], v[180:183], v[64:67]
	v_mfma_f32_16x16x32_bf16 v[116:119], v[192:195], v[160:163], v[116:119]
	v_mfma_f32_16x16x32_bf16 v[112:115], v[200:203], v[160:163], v[112:115]
	v_mfma_f32_16x16x32_bf16 v[100:103], v[192:195], v[168:171], v[100:103]
	v_mfma_f32_16x16x32_bf16 v[96:99], v[200:203], v[168:171], v[96:99]
	v_mfma_f32_16x16x32_bf16 v[84:87], v[192:195], v[176:179], v[84:87]
	v_mfma_f32_16x16x32_bf16 v[80:83], v[200:203], v[176:179], v[80:83]
	v_mfma_f32_16x16x32_bf16 v[68:71], v[192:195], v[184:187], v[68:71]
	s_setprio 0
	v_mfma_f32_16x16x32_bf16 v[64:67], v[200:203], v[184:187], v[64:67]
	s_barrier
; #define PG8_STAGE(bufoff, gbase, voff) do { _Pragma("unroll") for (int _i = 0; _i < 2; ++_i) \
;         __builtin_amdgcn_global_load_lds((const unsigned*)((const char*)(gbase) + (voff)[_i]), (LAS unsigned*)(lds + (bufoff) + ldsw + _i * 8192), 16, 0, 0); } while (0)
; #define PG8_LDA(dst, b, h) do { _Pragma("unroll") for (int m = 0; m < 4; ++m) _Pragma("unroll") for (int k = 0; k < 2; ++k) dst[m][k] = *(const LAS bf16x8*)(lds + PG8_SA(b, h) + aoff + m * 2048 + k * 1024); } while (0)
; #define PG8_WAIT_V(n) asm volatile("s_waitcnt vmcnt(" #n ")" ::: "memory")
; #define PG8_WAIT_L(n) asm volatile("s_waitcnt lgkmcnt(" #n ")" ::: "memory")
; template <class Epi>
; __device__ __forceinline__ void gemm_phase(LAS unsigned char* lds, const Gemm g, const StaticOrder& S, const Epi& E) {
;     ...
;         for (int t = 0; t < nt; t += 2) {
;             const bool last = (t == nt - 2);
;             const char* a1 = cA + (size_t)(t + 1) * kstep;
;             const char* a2 = last ? nA : cA + (size_t)(t + 2) * kstep; const char* b2 = last ? nB : cB + (size_t)(t + 2) * kstep;
;             const char* a3 = a2 + kstep; const char* b3 = b2 + kstep;
;             PG8_LDB(B0, 0, 0); PG8_SCHED; PG8_LDA(At, 0, 0); PG8_STAGE(PG8_SA(1, 1), a1 + hstepA, voffA);
;             PG8_WAIT_L(8); PG8_BAR; PG8_WAIT_L(0); PG8_MMA(0, 0, At, B0); PG8_BAR; PG8_SCHED;
;             PG8_LDB(B1, 0, 1); PG8_STAGE(PG8_SB(0, 0), b2, voffB);
;             PG8_BAR; PG8_WAIT_L(0); PG8_MMA(0, 1, At, B1); PG8_BAR;
;             PG8_LDA(At, 0, 1); PG8_STAGE(PG8_SA(0, 0), a2, voffA);
;             PG8_BAR; PG8_WAIT_L(0); PG8_MMA(1, 0, At, B0); PG8_BAR; PG8_SCHED;
;             PG8_STAGE(PG8_SB(0, 1), b2 + hstepB, voffB);
;             PG8_WAIT_V(6); PG8_BAR; PG8_MMA(1, 1, At, B1); PG8_BAR;
;             PG8_LDB(B0, 1, 0); PG8_SCHED; PG8_LDA(At, 1, 0); PG8_STAGE(PG8_SA(0, 1), a2 + hstepA, voffA);
;             PG8_WAIT_L(8); PG8_BAR; PG8_WAIT_L(0); PG8_MMA(0, 0, At, B0); PG8_BAR; PG8_SCHED;
;             PG8_LDB(B1, 1, 1); PG8_STAGE(PG8_SB(1, 0), b3, voffB);
;             PG8_BAR; PG8_WAIT_L(0); PG8_MMA(0, 1, At, B1); PG8_BAR;
;             PG8_LDA(At, 1, 1); PG8_STAGE(PG8_SA(1, 0), a3, voffA);
;             PG8_BAR; PG8_WAIT_L(0); PG8_MMA(1, 0, At, B0); PG8_BAR; PG8_SCHED;
;             PG8_STAGE(PG8_SB(1, 1), b3 + hstepB, voffB);
;             PG8_WAIT_V(6); PG8_BAR; PG8_MMA(1, 1, At, B1); PG8_BAR;
	s_mov_b32 m0, s55
	v_lshl_add_u64 v[204:205], s[28:29], 0, v[128:129]
	global_load_lds_dwordx4 v[204:205], off
	s_add_i32 m0, s55, 0x2000
	v_lshl_add_u64 v[204:205], s[28:29], 0, v[130:131]
	global_load_lds_dwordx4 v[204:205], off
	s_mov_b32 m0, s43
	v_lshl_add_u64 v[204:205], s[26:27], 0, v[128:129]
	global_load_lds_dwordx4 v[204:205], off
	s_mov_b32 m0, s44
	v_lshl_add_u64 v[204:205], s[26:27], 0, v[130:131]
	global_load_lds_dwordx4 v[204:205], off
	s_add_u32 s24, s24, 0x84000
	s_addc_u32 s25, s25, 0
	s_add_i32 s26, s56, s36
	s_mov_b32 m0, s26
	v_lshl_add_u64 v[204:205], s[24:25], 0, v[128:129]
	global_load_lds_dwordx4 v[204:205], off
	s_add_i32 m0, s26, 0x2000
	v_lshl_add_u64 v[204:205], s[24:25], 0, v[130:131]
	global_load_lds_dwordx4 v[204:205], off
	ds_read_b128 v[156:159], v135 offset:49152
	ds_read_b128 v[164:167], v135 offset:51200
	ds_read_b128 v[172:175], v135 offset:53248
	ds_read_b128 v[180:183], v135 offset:55296
	ds_read_b128 v[160:163], v135 offset:50176
	ds_read_b128 v[168:171], v135 offset:52224
	ds_read_b128 v[176:179], v135 offset:54272
	ds_read_b128 v[184:187], v135 offset:56320
	s_waitcnt vmcnt(6)
	s_waitcnt lgkmcnt(0)
	s_barrier
	v_mfma_f32_16x16x32_bf16 v[60:63], v[136:139], v[156:159], v[60:63]
	s_setprio 1
	v_mfma_f32_16x16x32_bf16 v[56:59], v[144:147], v[156:159], v[56:59]
	v_mfma_f32_16x16x32_bf16 v[44:47], v[136:139], v[164:167], v[44:47]
	v_mfma_f32_16x16x32_bf16 v[40:43], v[144:147], v[164:167], v[40:43]
	v_mfma_f32_16x16x32_bf16 v[28:31], v[136:139], v[172:175], v[28:31]
	v_mfma_f32_16x16x32_bf16 v[24:27], v[144:147], v[172:175], v[24:27]
	v_mfma_f32_16x16x32_bf16 v[12:15], v[136:139], v[180:183], v[12:15]
	v_mfma_f32_16x16x32_bf16 v[8:11], v[144:147], v[180:183], v[8:11]
	v_mfma_f32_16x16x32_bf16 v[60:63], v[140:143], v[160:163], v[60:63]
	v_mfma_f32_16x16x32_bf16 v[56:59], v[148:151], v[160:163], v[56:59]
	v_mfma_f32_16x16x32_bf16 v[44:47], v[140:143], v[168:171], v[44:47]
	v_mfma_f32_16x16x32_bf16 v[40:43], v[148:151], v[168:171], v[40:43]
	v_mfma_f32_16x16x32_bf16 v[28:31], v[140:143], v[176:179], v[28:31]
	v_mfma_f32_16x16x32_bf16 v[24:27], v[148:151], v[176:179], v[24:27]
	v_mfma_f32_16x16x32_bf16 v[12:15], v[140:143], v[184:187], v[12:15]
	v_mfma_f32_16x16x32_bf16 v[8:11], v[148:151], v[184:187], v[8:11]
	v_mfma_f32_16x16x32_bf16 v[52:55], v[188:191], v[156:159], v[52:55]
	v_mfma_f32_16x16x32_bf16 v[48:51], v[196:199], v[156:159], v[48:51]
	s_add_i32 s54, s54, 2
	s_add_u32 s22, s22, 0x8000
	s_addc_u32 s23, s23, 0
	s_add_u32 s51, s51, 0x8000
	s_addc_u32 s52, s52, 0
	v_mfma_f32_16x16x32_bf16 v[36:39], v[188:191], v[164:167], v[36:39]
	v_mfma_f32_16x16x32_bf16 v[32:35], v[196:199], v[164:167], v[32:35]
	v_mfma_f32_16x16x32_bf16 v[20:23], v[188:191], v[172:175], v[20:23]
	v_mfma_f32_16x16x32_bf16 v[16:19], v[196:199], v[172:175], v[16:19]
	v_mfma_f32_16x16x32_bf16 v[4:7], v[188:191], v[180:183], v[4:7]
	v_mfma_f32_16x16x32_bf16 v[0:3], v[196:199], v[180:183], v[0:3]
	v_mfma_f32_16x16x32_bf16 v[52:55], v[192:195], v[160:163], v[52:55]
	v_mfma_f32_16x16x32_bf16 v[48:51], v[200:203], v[160:163], v[48:51]
	v_mfma_f32_16x16x32_bf16 v[36:39], v[192:195], v[168:171], v[36:39]
	v_mfma_f32_16x16x32_bf16 v[32:35], v[200:203], v[168:171], v[32:35]
	v_mfma_f32_16x16x32_bf16 v[20:23], v[192:195], v[176:179], v[20:23]
	v_mfma_f32_16x16x32_bf16 v[16:19], v[200:203], v[176:179], v[16:19]
	v_mfma_f32_16x16x32_bf16 v[4:7], v[192:195], v[184:187], v[4:7]
	s_cmp_gt_u32 s54, 29
	s_setprio 0
	v_mfma_f32_16x16x32_bf16 v[0:3], v[200:203], v[184:187], v[0:3]
	s_barrier
	s_cbranch_scc0 .LBB0_141
	s_branch .Lpeel_done_141
.LBB0_141:
	s_add_u32 s24, s22, 0xfff84000
	s_addc_u32 s25, s23, -1
	s_cmp_eq_u32 s54, 28
	s_cselect_b32 s28, s49, s24
	s_cselect_b32 s29, s15, s25
	s_cselect_b32 s24, s50, s51
	s_cselect_b32 s25, s5, s52
	s_add_u32 s26, s28, 0x4000
	s_addc_u32 s27, s29, 0
	s_add_i32 m0, s37, 0xc000
	v_lshl_add_u64 v[188:189], s[22:23], 0, v[128:129]
	global_load_lds_dwordx4 v[188:189], off
	s_add_i32 m0, s37, 0xe000
	v_lshl_add_u64 v[188:189], s[22:23], 0, v[130:131]
	global_load_lds_dwordx4 v[188:189], off
	s_mov_b32 s55, 0x10000
	v_add_u32_e32 v148, s55, v134
	ds_read_b128 v[136:139], v148
	ds_read_b128 v[144:147], v148 offset:2048
	ds_read_b128 v[140:143], v148 offset:1024
	ds_read_b128 v[148:151], v148 offset:3072
	ds_read_b128 v[156:159], v135
	ds_read_b128 v[164:167], v135 offset:2048
	ds_read_b128 v[172:175], v135 offset:4096
	ds_read_b128 v[180:183], v135 offset:6144
	ds_read_b128 v[160:163], v135 offset:1024
	ds_read_b128 v[168:171], v135 offset:3072
	ds_read_b128 v[176:179], v135 offset:5120
	ds_read_b128 v[184:187], v135 offset:7168
	s_mov_b32 s58, 0x14000
	s_add_i32 s55, s55, s36
	v_add_u32_e32 v152, s58, v134
	ds_read_b128 v[188:191], v152
	ds_read_b128 v[196:199], v152 offset:2048
	ds_read_b128 v[192:195], v152 offset:1024
	ds_read_b128 v[200:203], v152 offset:3072
	s_waitcnt lgkmcnt(0)
	s_barrier
; #define PG8_STAGE(bufoff, gbase, voff) do { _Pragma("unroll") for (int _i = 0; _i < 2; ++_i) \
;         __builtin_amdgcn_global_load_lds((const unsigned*)((const char*)(gbase) + (voff)[_i]), (LAS unsigned*)(lds + (bufoff) + ldsw + _i * 8192), 16, 0, 0); } while (0)
; #define PG8_LDA(dst, b, h) do { _Pragma("unroll") for (int m = 0; m < 4; ++m) _Pragma("unroll") for (int k = 0; k < 2; ++k) dst[m][k] = *(const LAS bf16x8*)(lds + PG8_SA(b, h) + aoff + m * 2048 + k * 1024); } while (0)
; #define PG8_LDB(dst, b, h) do { _Pragma("unroll") for (int n = 0; n < 2; ++n) _Pragma("unroll") for (int k = 0; k < 2; ++k) dst[n][k] = *(const LAS bf16x8*)(lds + PG8_SB(b, h) + boff + n * 2048 + k * 1024); } while (0)
; #define PG8_MMA(ai, bj, At, Bt) do { __builtin_amdgcn_s_setprio(1); _Pragma("unroll") for (int m = 0; m < 4; ++m) _Pragma("unroll") for (int n = 0; n < 2; ++n) _Pragma("unroll") for (int k = 0; k < 2; ++k) \
;         acc[ai][bj][m][n] = __builtin_amdgcn_mfma_f32_16x16x32_bf16(Bt[n][k], At[m][k], acc[ai][bj][m][n], 0, 0, 0); __builtin_amdgcn_s_setprio(0); } while (0)
; #define PG8_WAIT_V(n) asm volatile("s_waitcnt vmcnt(" #n ")" ::: "memory")
; #define PG8_WAIT_L(n) asm volatile("s_waitcnt lgkmcnt(" #n ")" ::: "memory")
; #define PG8_BAR __builtin_amdgcn_s_barrier()
; #define PG8_SCHED __builtin_amdgcn_sched_barrier(0)
; template <class Epi>
; __device__ __forceinline__ void gemm_phase(LAS unsigned char* lds, const Gemm g, const StaticOrder& S, const Epi& E) {
;     ...
;             PG8_WAIT_L(8); PG8_BAR; PG8_WAIT_L(0); PG8_MMA(0, 0, At, B0); PG8_BAR; PG8_SCHED;
;             PG8_LDB(B1, 0, 1); PG8_STAGE(PG8_SB(0, 0), b2, voffB);
;             PG8_BAR; PG8_WAIT_L(0); PG8_MMA(0, 1, At, B1); PG8_BAR;
;             PG8_LDA(At, 0, 1); PG8_STAGE(PG8_SA(0, 0), a2, voffA);
;             PG8_BAR; PG8_WAIT_L(0); PG8_MMA(1, 0, At, B0); PG8_BAR; PG8_SCHED;
;             PG8_STAGE(PG8_SB(0, 1), b2 + hstepB, voffB);
;             PG8_WAIT_V(6); PG8_BAR; PG8_MMA(1, 1, At, B1); PG8_BAR;
	v_mfma_f32_16x16x32_bf16 v[124:127], v[136:139], v[156:159], v[124:127]
	s_setprio 1
	v_mfma_f32_16x16x32_bf16 v[120:123], v[144:147], v[156:159], v[120:123]
	v_mfma_f32_16x16x32_bf16 v[108:111], v[136:139], v[164:167], v[108:111]
	v_mfma_f32_16x16x32_bf16 v[104:107], v[144:147], v[164:167], v[104:107]
	v_mfma_f32_16x16x32_bf16 v[92:95], v[136:139], v[172:175], v[92:95]
	v_mfma_f32_16x16x32_bf16 v[88:91], v[144:147], v[172:175], v[88:91]
	v_mfma_f32_16x16x32_bf16 v[76:79], v[136:139], v[180:183], v[76:79]
	v_mfma_f32_16x16x32_bf16 v[72:75], v[144:147], v[180:183], v[72:75]
	v_mfma_f32_16x16x32_bf16 v[124:127], v[140:143], v[160:163], v[124:127]
	v_mfma_f32_16x16x32_bf16 v[120:123], v[148:151], v[160:163], v[120:123]
	v_mfma_f32_16x16x32_bf16 v[108:111], v[140:143], v[168:171], v[108:111]
	v_mfma_f32_16x16x32_bf16 v[104:107], v[148:151], v[168:171], v[104:107]
	v_mfma_f32_16x16x32_bf16 v[92:95], v[140:143], v[176:179], v[92:95]
	v_mfma_f32_16x16x32_bf16 v[88:91], v[148:151], v[176:179], v[88:91]
	v_mfma_f32_16x16x32_bf16 v[76:79], v[140:143], v[184:187], v[76:79]
	v_mfma_f32_16x16x32_bf16 v[72:75], v[148:151], v[184:187], v[72:75]
	v_mfma_f32_16x16x32_bf16 v[116:119], v[188:191], v[156:159], v[116:119]
	v_mfma_f32_16x16x32_bf16 v[112:115], v[196:199], v[156:159], v[112:115]
	v_mfma_f32_16x16x32_bf16 v[100:103], v[188:191], v[164:167], v[100:103]
	v_mfma_f32_16x16x32_bf16 v[96:99], v[196:199], v[164:167], v[96:99]
	v_mfma_f32_16x16x32_bf16 v[84:87], v[188:191], v[172:175], v[84:87]
	v_mfma_f32_16x16x32_bf16 v[80:83], v[196:199], v[172:175], v[80:83]
	v_mfma_f32_16x16x32_bf16 v[68:71], v[188:191], v[180:183], v[68:71]
	v_mfma_f32_16x16x32_bf16 v[64:67], v[196:199], v[180:183], v[64:67]
	v_mfma_f32_16x16x32_bf16 v[116:119], v[192:195], v[160:163], v[116:119]
	v_mfma_f32_16x16x32_bf16 v[112:115], v[200:203], v[160:163], v[112:115]
	v_mfma_f32_16x16x32_bf16 v[100:103], v[192:195], v[168:171], v[100:103]
	v_mfma_f32_16x16x32_bf16 v[96:99], v[200:203], v[168:171], v[96:99]
	v_mfma_f32_16x16x32_bf16 v[84:87], v[192:195], v[176:179], v[84:87]
	v_mfma_f32_16x16x32_bf16 v[80:83], v[200:203], v[176:179], v[80:83]
	v_mfma_f32_16x16x32_bf16 v[68:71], v[192:195], v[184:187], v[68:71]
	s_setprio 0
	v_mfma_f32_16x16x32_bf16 v[64:67], v[200:203], v[184:187], v[64:67]
	s_barrier
	s_mov_b32 m0, s55
	v_lshl_add_u64 v[204:205], s[24:25], 0, v[128:129]
	global_load_lds_dwordx4 v[204:205], off
	s_add_i32 m0, s55, 0x2000
	v_lshl_add_u64 v[204:205], s[24:25], 0, v[130:131]
	global_load_lds_dwordx4 v[204:205], off
	s_mov_b32 m0, s37
	v_lshl_add_u64 v[204:205], s[28:29], 0, v[128:129]
	global_load_lds_dwordx4 v[204:205], off
	s_mov_b32 m0, s38
	v_lshl_add_u64 v[204:205], s[28:29], 0, v[130:131]
	global_load_lds_dwordx4 v[204:205], off
	s_add_u32 s56, s24, 0x80000
	s_addc_u32 s57, s25, 0
	s_add_i32 s55, s58, s36
	s_mov_b32 m0, s55
	v_lshl_add_u64 v[204:205], s[56:57], 0, v[128:129]
	global_load_lds_dwordx4 v[204:205], off
	s_add_i32 m0, s55, 0x2000
	v_lshl_add_u64 v[204:205], s[56:57], 0, v[130:131]
	global_load_lds_dwordx4 v[204:205], off
	ds_read_b128 v[156:159], v135 offset:16384
	ds_read_b128 v[164:167], v135 offset:18432
	ds_read_b128 v[172:175], v135 offset:20480
	ds_read_b128 v[180:183], v135 offset:22528
	ds_read_b128 v[160:163], v135 offset:17408
	ds_read_b128 v[168:171], v135 offset:19456
	ds_read_b128 v[176:179], v135 offset:21504
	ds_read_b128 v[184:187], v135 offset:23552
	s_waitcnt vmcnt(6)
	s_waitcnt lgkmcnt(0)
	s_barrier
	v_mfma_f32_16x16x32_bf16 v[60:63], v[136:139], v[156:159], v[60:63]
	s_setprio 1
	v_mfma_f32_16x16x32_bf16 v[56:59], v[144:147], v[156:159], v[56:59]
	v_mfma_f32_16x16x32_bf16 v[44:47], v[136:139], v[164:167], v[44:47]
	v_mfma_f32_16x16x32_bf16 v[40:43], v[144:147], v[164:167], v[40:43]
	v_mfma_f32_16x16x32_bf16 v[28:31], v[136:139], v[172:175], v[28:31]
	v_mfma_f32_16x16x32_bf16 v[24:27], v[144:147], v[172:175], v[24:27]
	v_mfma_f32_16x16x32_bf16 v[12:15], v[136:139], v[180:183], v[12:15]
	v_mfma_f32_16x16x32_bf16 v[8:11], v[144:147], v[180:183], v[8:11]
	v_mfma_f32_16x16x32_bf16 v[60:63], v[140:143], v[160:163], v[60:63]
	v_mfma_f32_16x16x32_bf16 v[56:59], v[148:151], v[160:163], v[56:59]
	v_mfma_f32_16x16x32_bf16 v[44:47], v[140:143], v[168:171], v[44:47]
	v_mfma_f32_16x16x32_bf16 v[40:43], v[148:151], v[168:171], v[40:43]
	v_mfma_f32_16x16x32_bf16 v[28:31], v[140:143], v[176:179], v[28:31]
	v_mfma_f32_16x16x32_bf16 v[24:27], v[148:151], v[176:179], v[24:27]
	v_mfma_f32_16x16x32_bf16 v[12:15], v[140:143], v[184:187], v[12:15]
	v_mfma_f32_16x16x32_bf16 v[8:11], v[148:151], v[184:187], v[8:11]
	v_mfma_f32_16x16x32_bf16 v[52:55], v[188:191], v[156:159], v[52:55]
	v_mfma_f32_16x16x32_bf16 v[48:51], v[196:199], v[156:159], v[48:51]
	s_add_i32 s55, 0, 0x18000
	v_add_u32_e32 v148, s55, v134
	v_mfma_f32_16x16x32_bf16 v[36:39], v[188:191], v[164:167], v[36:39]
	v_mfma_f32_16x16x32_bf16 v[32:35], v[196:199], v[164:167], v[32:35]
	v_mfma_f32_16x16x32_bf16 v[20:23], v[188:191], v[172:175], v[20:23]
	v_mfma_f32_16x16x32_bf16 v[16:19], v[196:199], v[172:175], v[16:19]
	v_mfma_f32_16x16x32_bf16 v[4:7], v[188:191], v[180:183], v[4:7]
	v_mfma_f32_16x16x32_bf16 v[0:3], v[196:199], v[180:183], v[0:3]
	v_mfma_f32_16x16x32_bf16 v[52:55], v[192:195], v[160:163], v[52:55]
	v_mfma_f32_16x16x32_bf16 v[48:51], v[200:203], v[160:163], v[48:51]
	v_mfma_f32_16x16x32_bf16 v[36:39], v[192:195], v[168:171], v[36:39]
	v_mfma_f32_16x16x32_bf16 v[32:35], v[200:203], v[168:171], v[32:35]
	v_mfma_f32_16x16x32_bf16 v[20:23], v[192:195], v[176:179], v[20:23]
	v_mfma_f32_16x16x32_bf16 v[16:19], v[200:203], v[176:179], v[16:19]
	v_mfma_f32_16x16x32_bf16 v[4:7], v[192:195], v[184:187], v[4:7]
	s_setprio 0
	v_mfma_f32_16x16x32_bf16 v[0:3], v[200:203], v[184:187], v[0:3]
	s_barrier
; #define PG8_STAGE(bufoff, gbase, voff) do { _Pragma("unroll") for (int _i = 0; _i < 2; ++_i) \
;         __builtin_amdgcn_global_load_lds((const unsigned*)((const char*)(gbase) + (voff)[_i]), (LAS unsigned*)(lds + (bufoff) + ldsw + _i * 8192), 16, 0, 0); } while (0)
; #define PG8_LDA(dst, b, h) do { _Pragma("unroll") for (int m = 0; m < 4; ++m) _Pragma("unroll") for (int k = 0; k < 2; ++k) dst[m][k] = *(const LAS bf16x8*)(lds + PG8_SA(b, h) + aoff + m * 2048 + k * 1024); } while (0)
; #define PG8_LDB(dst, b, h) do { _Pragma("unroll") for (int n = 0; n < 2; ++n) _Pragma("unroll") for (int k = 0; k < 2; ++k) dst[n][k] = *(const LAS bf16x8*)(lds + PG8_SB(b, h) + boff + n * 2048 + k * 1024); } while (0)
; #define PG8_MMA(ai, bj, At, Bt) do { __builtin_amdgcn_s_setprio(1); _Pragma("unroll") for (int m = 0; m < 4; ++m) _Pragma("unroll") for (int n = 0; n < 2; ++n) _Pragma("unroll") for (int k = 0; k < 2; ++k) \
;         acc[ai][bj][m][n] = __builtin_amdgcn_mfma_f32_16x16x32_bf16(Bt[n][k], At[m][k], acc[ai][bj][m][n], 0, 0, 0); __builtin_amdgcn_s_setprio(0); } while (0)
; #define PG8_WAIT_V(n) asm volatile("s_waitcnt vmcnt(" #n ")" ::: "memory")
; #define PG8_WAIT_L(n) asm volatile("s_waitcnt lgkmcnt(" #n ")" ::: "memory")
; #define PG8_BAR __builtin_amdgcn_s_barrier()
; #define PG8_SCHED __builtin_amdgcn_sched_barrier(0)
; template <class Epi>
; __device__ __forceinline__ void gemm_phase(LAS unsigned char* lds, const Gemm g, const StaticOrder& S, const Epi& E) {
;     ...
;             PG8_LDB(B0, 1, 0); PG8_SCHED; PG8_LDA(At, 1, 0); PG8_STAGE(PG8_SA(0, 1), a2 + hstepA, voffA);
;             PG8_WAIT_L(8); PG8_BAR; PG8_WAIT_L(0); PG8_MMA(0, 0, At, B0); PG8_BAR; PG8_SCHED;
;             PG8_LDB(B1, 1, 1); PG8_STAGE(PG8_SB(1, 0), b3, voffB);
;             PG8_BAR; PG8_WAIT_L(0); PG8_MMA(0, 1, At, B1); PG8_BAR;
;             PG8_LDA(At, 1, 1); PG8_STAGE(PG8_SA(1, 0), a3, voffA);
;             PG8_BAR; PG8_WAIT_L(0); PG8_MMA(1, 0, At, B0); PG8_BAR; PG8_SCHED;
;             PG8_STAGE(PG8_SB(1, 1), b3 + hstepB, voffB);
;             PG8_WAIT_V(6); PG8_BAR; PG8_MMA(1, 1, At, B1); PG8_BAR;
	s_add_u32 s28, s28, 0x80000
	s_addc_u32 s29, s29, 0
	s_mov_b32 m0, s39
	v_lshl_add_u64 v[188:189], s[28:29], 0, v[128:129]
	global_load_lds_dwordx4 v[188:189], off
	s_mov_b32 m0, s40
	v_lshl_add_u64 v[188:189], s[28:29], 0, v[130:131]
	global_load_lds_dwordx4 v[188:189], off
	ds_read_b128 v[136:139], v148
	ds_read_b128 v[144:147], v148 offset:2048
	ds_read_b128 v[140:143], v148 offset:1024
	ds_read_b128 v[148:151], v148 offset:3072
	ds_read_b128 v[156:159], v135 offset:32768
	ds_read_b128 v[164:167], v135 offset:34816
	ds_read_b128 v[172:175], v135 offset:36864
	ds_read_b128 v[180:183], v135 offset:38912
	ds_read_b128 v[160:163], v135 offset:33792
	ds_read_b128 v[168:171], v135 offset:35840
	ds_read_b128 v[176:179], v135 offset:37888
	ds_read_b128 v[184:187], v135 offset:39936
	s_mov_b32 s56, 0x1c000
	s_add_u32 s28, s24, 0x4000
	s_addc_u32 s29, s25, 0
	s_add_i32 s55, s55, s36
	v_add_u32_e32 v152, s56, v134
	ds_read_b128 v[188:191], v152
	ds_read_b128 v[196:199], v152 offset:2048
	ds_read_b128 v[192:195], v152 offset:1024
	ds_read_b128 v[200:203], v152 offset:3072
	s_waitcnt lgkmcnt(0)
	s_barrier
	v_mfma_f32_16x16x32_bf16 v[124:127], v[136:139], v[156:159], v[124:127]
	s_setprio 1
	v_mfma_f32_16x16x32_bf16 v[120:123], v[144:147], v[156:159], v[120:123]
	v_mfma_f32_16x16x32_bf16 v[108:111], v[136:139], v[164:167], v[108:111]
	v_mfma_f32_16x16x32_bf16 v[104:107], v[144:147], v[164:167], v[104:107]
	v_mfma_f32_16x16x32_bf16 v[92:95], v[136:139], v[172:175], v[92:95]
	v_mfma_f32_16x16x32_bf16 v[88:91], v[144:147], v[172:175], v[88:91]
	v_mfma_f32_16x16x32_bf16 v[76:79], v[136:139], v[180:183], v[76:79]
	v_mfma_f32_16x16x32_bf16 v[72:75], v[144:147], v[180:183], v[72:75]
	v_mfma_f32_16x16x32_bf16 v[124:127], v[140:143], v[160:163], v[124:127]
	v_mfma_f32_16x16x32_bf16 v[120:123], v[148:151], v[160:163], v[120:123]
	v_mfma_f32_16x16x32_bf16 v[108:111], v[140:143], v[168:171], v[108:111]
	v_mfma_f32_16x16x32_bf16 v[104:107], v[148:151], v[168:171], v[104:107]
	v_mfma_f32_16x16x32_bf16 v[92:95], v[140:143], v[176:179], v[92:95]
	v_mfma_f32_16x16x32_bf16 v[88:91], v[148:151], v[176:179], v[88:91]
	v_mfma_f32_16x16x32_bf16 v[76:79], v[140:143], v[184:187], v[76:79]
	v_mfma_f32_16x16x32_bf16 v[72:75], v[148:151], v[184:187], v[72:75]
	v_mfma_f32_16x16x32_bf16 v[116:119], v[188:191], v[156:159], v[116:119]
	v_mfma_f32_16x16x32_bf16 v[112:115], v[196:199], v[156:159], v[112:115]
	v_mfma_f32_16x16x32_bf16 v[100:103], v[188:191], v[164:167], v[100:103]
	v_mfma_f32_16x16x32_bf16 v[96:99], v[196:199], v[164:167], v[96:99]
	v_mfma_f32_16x16x32_bf16 v[84:87], v[188:191], v[172:175], v[84:87]
	v_mfma_f32_16x16x32_bf16 v[80:83], v[196:199], v[172:175], v[80:83]
	v_mfma_f32_16x16x32_bf16 v[68:71], v[188:191], v[180:183], v[68:71]
	v_mfma_f32_16x16x32_bf16 v[64:67], v[196:199], v[180:183], v[64:67]
	v_mfma_f32_16x16x32_bf16 v[116:119], v[192:195], v[160:163], v[116:119]
	v_mfma_f32_16x16x32_bf16 v[112:115], v[200:203], v[160:163], v[112:115]
	v_mfma_f32_16x16x32_bf16 v[100:103], v[192:195], v[168:171], v[100:103]
	v_mfma_f32_16x16x32_bf16 v[96:99], v[200:203], v[168:171], v[96:99]
	v_mfma_f32_16x16x32_bf16 v[84:87], v[192:195], v[176:179], v[84:87]
	v_mfma_f32_16x16x32_bf16 v[80:83], v[200:203], v[176:179], v[80:83]
	v_mfma_f32_16x16x32_bf16 v[68:71], v[192:195], v[184:187], v[68:71]
	s_setprio 0
	v_mfma_f32_16x16x32_bf16 v[64:67], v[200:203], v[184:187], v[64:67]
	s_barrier
	s_mov_b32 m0, s55
	v_lshl_add_u64 v[204:205], s[28:29], 0, v[128:129]
	global_load_lds_dwordx4 v[204:205], off
	s_add_i32 m0, s55, 0x2000
	v_lshl_add_u64 v[204:205], s[28:29], 0, v[130:131]
	global_load_lds_dwordx4 v[204:205], off
	s_mov_b32 m0, s43
	v_lshl_add_u64 v[204:205], s[26:27], 0, v[128:129]
	global_load_lds_dwordx4 v[204:205], off
	s_mov_b32 m0, s44
	v_lshl_add_u64 v[204:205], s[26:27], 0, v[130:131]
	global_load_lds_dwordx4 v[204:205], off
	s_add_u32 s24, s24, 0x84000
	s_addc_u32 s25, s25, 0
	s_add_i32 s26, s56, s36
	s_mov_b32 m0, s26
	v_lshl_add_u64 v[204:205], s[24:25], 0, v[128:129]
	global_load_lds_dwordx4 v[204:205], off
	s_add_i32 m0, s26, 0x2000
	v_lshl_add_u64 v[204:205], s[24:25], 0, v[130:131]
	global_load_lds_dwordx4 v[204:205], off
	ds_read_b128 v[156:159], v135 offset:49152
	ds_read_b128 v[164:167], v135 offset:51200
	ds_read_b128 v[172:175], v135 offset:53248
	ds_read_b128 v[180:183], v135 offset:55296
	ds_read_b128 v[160:163], v135 offset:50176
	ds_read_b128 v[168:171], v135 offset:52224
	ds_read_b128 v[176:179], v135 offset:54272
	ds_read_b128 v[184:187], v135 offset:56320
	s_waitcnt vmcnt(6)
	s_waitcnt lgkmcnt(0)
	s_barrier
	v_mfma_f32_16x16x32_bf16 v[60:63], v[136:139], v[156:159], v[60:63]
	s_setprio 1
	v_mfma_f32_16x16x32_bf16 v[56:59], v[144:147], v[156:159], v[56:59]
	v_mfma_f32_16x16x32_bf16 v[44:47], v[136:139], v[164:167], v[44:47]
	v_mfma_f32_16x16x32_bf16 v[40:43], v[144:147], v[164:167], v[40:43]
	v_mfma_f32_16x16x32_bf16 v[28:31], v[136:139], v[172:175], v[28:31]
	v_mfma_f32_16x16x32_bf16 v[24:27], v[144:147], v[172:175], v[24:27]
	v_mfma_f32_16x16x32_bf16 v[12:15], v[136:139], v[180:183], v[12:15]
	v_mfma_f32_16x16x32_bf16 v[8:11], v[144:147], v[180:183], v[8:11]
	v_mfma_f32_16x16x32_bf16 v[60:63], v[140:143], v[160:163], v[60:63]
	v_mfma_f32_16x16x32_bf16 v[56:59], v[148:151], v[160:163], v[56:59]
	v_mfma_f32_16x16x32_bf16 v[44:47], v[140:143], v[168:171], v[44:47]
	v_mfma_f32_16x16x32_bf16 v[40:43], v[148:151], v[168:171], v[40:43]
	v_mfma_f32_16x16x32_bf16 v[28:31], v[140:143], v[176:179], v[28:31]
	v_mfma_f32_16x16x32_bf16 v[24:27], v[148:151], v[176:179], v[24:27]
	v_mfma_f32_16x16x32_bf16 v[12:15], v[140:143], v[184:187], v[12:15]
	v_mfma_f32_16x16x32_bf16 v[8:11], v[148:151], v[184:187], v[8:11]
	v_mfma_f32_16x16x32_bf16 v[52:55], v[188:191], v[156:159], v[52:55]
	v_mfma_f32_16x16x32_bf16 v[48:51], v[196:199], v[156:159], v[48:51]
	s_add_i32 s54, s54, 2
	s_add_u32 s22, s22, 0x8000
	s_addc_u32 s23, s23, 0
	s_add_u32 s51, s51, 0x8000
	s_addc_u32 s52, s52, 0
	v_mfma_f32_16x16x32_bf16 v[36:39], v[188:191], v[164:167], v[36:39]
	v_mfma_f32_16x16x32_bf16 v[32:35], v[196:199], v[164:167], v[32:35]
	v_mfma_f32_16x16x32_bf16 v[20:23], v[188:191], v[172:175], v[20:23]
	v_mfma_f32_16x16x32_bf16 v[16:19], v[196:199], v[172:175], v[16:19]
	v_mfma_f32_16x16x32_bf16 v[4:7], v[188:191], v[180:183], v[4:7]
	v_mfma_f32_16x16x32_bf16 v[0:3], v[196:199], v[180:183], v[0:3]
	v_mfma_f32_16x16x32_bf16 v[52:55], v[192:195], v[160:163], v[52:55]
	v_mfma_f32_16x16x32_bf16 v[48:51], v[200:203], v[160:163], v[48:51]
	v_mfma_f32_16x16x32_bf16 v[36:39], v[192:195], v[168:171], v[36:39]
	v_mfma_f32_16x16x32_bf16 v[32:35], v[200:203], v[168:171], v[32:35]
	v_mfma_f32_16x16x32_bf16 v[20:23], v[192:195], v[176:179], v[20:23]
	v_mfma_f32_16x16x32_bf16 v[16:19], v[200:203], v[176:179], v[16:19]
	v_mfma_f32_16x16x32_bf16 v[4:7], v[192:195], v[184:187], v[4:7]
	s_cmp_gt_u32 s54, 29
	s_setprio 0
	v_mfma_f32_16x16x32_bf16 v[0:3], v[200:203], v[184:187], v[0:3]
	s_barrier
	s_cbranch_scc0 .LBB0_141

; #define PG8_STAGE(bufoff, gbase, voff) do { _Pragma("unroll") for (int _i = 0; _i < 2; ++_i) \
;         __builtin_amdgcn_global_load_lds((const unsigned*)((const char*)(gbase) + (voff)[_i]), (LAS unsigned*)(lds + (bufoff) + ldsw + _i * 8192), 16, 0, 0); } while (0)
; #define PG8_LDA(dst, b, h) do { _Pragma("unroll") for (int m = 0; m < 4; ++m) _Pragma("unroll") for (int k = 0; k < 2; ++k) dst[m][k] = *(const LAS bf16x8*)(lds + PG8_SA(b, h) + aoff + m * 2048 + k * 1024); } while (0)
; #define PG8_LDB(dst, b, h) do { _Pragma("unroll") for (int n = 0; n < 2; ++n) _Pragma("unroll") for (int k = 0; k < 2; ++k) dst[n][k] = *(const LAS bf16x8*)(lds + PG8_SB(b, h) + boff + n * 2048 + k * 1024); } while (0)
; #define PG8_WAIT_V(n) asm volatile("s_waitcnt vmcnt(" #n ")" ::: "memory")
; #define PG8_WAIT_L(n) asm volatile("s_waitcnt lgkmcnt(" #n ")" ::: "memory")
; #define PG8_BAR __builtin_amdgcn_s_barrier()
; #define PG8_SCHED __builtin_amdgcn_sched_barrier(0)
; template <class Epi>
; __device__ __forceinline__ void gemm_phase(LAS unsigned char* lds, const Gemm g, const StaticOrder& S, const Epi& E) {
;     ...
;         const bool has_next = S.next(ui + 1, nxt);
;         const char* nA = has_next ? (const char*)g.A + (size_t)nxt.pm * tstepA : cA; const char* nB = has_next ? (const char*)g.Bt + (size_t)nxt.pn * tstepB : cB;
;         for (int t = 0; t < nt; t += 2) {
;             const bool last = (t == nt - 2);
;             const char* a1 = cA + (size_t)(t + 1) * kstep;
;             const char* a2 = last ? nA : cA + (size_t)(t + 2) * kstep; const char* b2 = last ? nB : cB + (size_t)(t + 2) * kstep;
;             const char* a3 = a2 + kstep; const char* b3 = b2 + kstep;
;             PG8_LDB(B0, 0, 0); PG8_SCHED; PG8_LDA(At, 0, 0); PG8_STAGE(PG8_SA(1, 1), a1 + hstepA, voffA);
;             PG8_WAIT_L(8); PG8_BAR; PG8_WAIT_L(0); PG8_MMA(0, 0, At, B0); PG8_BAR; PG8_SCHED;
;             PG8_LDB(B1, 0, 1); PG8_STAGE(PG8_SB(0, 0), b2, voffB);
;             PG8_BAR; PG8_WAIT_L(0); PG8_MMA(0, 1, At, B1); PG8_BAR;
;             PG8_LDA(At, 0, 1); PG8_STAGE(PG8_SA(0, 0), a2, voffA);
;             PG8_BAR; PG8_WAIT_L(0); PG8_MMA(1, 0, At, B0); PG8_BAR; PG8_SCHED;
;             PG8_STAGE(PG8_SB(0, 1), b2 + hstepB, voffB);
;             PG8_WAIT_V(6); PG8_BAR; PG8_MMA(1, 1, At, B1); PG8_BAR;
.LBB0_186:
	s_add_u32 s4, s24, 0x4000
	s_addc_u32 s5, s25, 0
	s_add_u32 s50, s22, 0x8000
	s_addc_u32 s51, s23, 0
	s_mov_b32 s22, 0
	s_add_i32 s54, s22, 2
	s_add_u32 s23, s4, 0x4000
	s_addc_u32 s24, s5, 0
	s_cmp_eq_u32 s40, s22
	s_cselect_b32 s26, s6, s23
	s_cselect_b32 s27, s7, s24
	s_cselect_b32 s24, s20, s50
	s_cselect_b32 s25, s21, s51
	s_add_u32 s22, s26, 0x4000
	s_addc_u32 s23, s27, 0
	s_add_i32 m0, s33, 0xc000
	v_lshl_add_u64 v[186:187], s[4:5], 0, v[158:159]
	global_load_lds_dwordx4 v[186:187], off
	s_add_i32 m0, s33, 0xe000
	v_lshl_add_u64 v[186:187], s[4:5], 0, v[160:161]
	global_load_lds_dwordx4 v[186:187], off
	s_mov_b32 s55, 0x10000
	v_add_u32_e32 v140, s55, v207
	ds_read_b128 v[128:131], v140
	ds_read_b128 v[136:139], v140 offset:2048
	ds_read_b128 v[132:135], v140 offset:1024
	ds_read_b128 v[140:143], v140 offset:3072
	ds_read_b128 v[144:147], v209
	ds_read_b128 v[162:165], v209 offset:2048
	ds_read_b128 v[170:173], v209 offset:4096
	ds_read_b128 v[178:181], v209 offset:6144
	ds_read_b128 v[148:151], v209 offset:1024
	ds_read_b128 v[166:169], v209 offset:3072
	ds_read_b128 v[174:177], v209 offset:5120
	ds_read_b128 v[182:185], v209 offset:7168
	s_mov_b32 s58, 0x14000
	s_add_i32 s55, s55, s31
	v_add_u32_e32 v198, s58, v207
	ds_read_b128 v[186:189], v198
	ds_read_b128 v[194:197], v198 offset:2048
	ds_read_b128 v[190:193], v198 offset:1024
	ds_read_b128 v[198:201], v198 offset:3072
	s_waitcnt lgkmcnt(0)
	s_barrier
	v_mfma_f32_16x16x32_bf16 v[124:127], v[128:131], v[144:147], 0
	s_setprio 1
	v_mfma_f32_16x16x32_bf16 v[120:123], v[136:139], v[144:147], 0
	v_mfma_f32_16x16x32_bf16 v[116:119], v[128:131], v[162:165], 0
	v_mfma_f32_16x16x32_bf16 v[112:115], v[136:139], v[162:165], 0
	v_mfma_f32_16x16x32_bf16 v[108:111], v[128:131], v[170:173], 0
	v_mfma_f32_16x16x32_bf16 v[104:107], v[136:139], v[170:173], 0
	v_mfma_f32_16x16x32_bf16 v[100:103], v[128:131], v[178:181], 0
	v_mfma_f32_16x16x32_bf16 v[96:99], v[136:139], v[178:181], 0
	v_mfma_f32_16x16x32_bf16 v[124:127], v[132:135], v[148:151], v[124:127]
	v_mfma_f32_16x16x32_bf16 v[120:123], v[140:143], v[148:151], v[120:123]
	v_mfma_f32_16x16x32_bf16 v[116:119], v[132:135], v[166:169], v[116:119]
	v_mfma_f32_16x16x32_bf16 v[112:115], v[140:143], v[166:169], v[112:115]
	v_mfma_f32_16x16x32_bf16 v[108:111], v[132:135], v[174:177], v[108:111]
	v_mfma_f32_16x16x32_bf16 v[104:107], v[140:143], v[174:177], v[104:107]
	v_mfma_f32_16x16x32_bf16 v[100:103], v[132:135], v[182:185], v[100:103]
	v_mfma_f32_16x16x32_bf16 v[96:99], v[140:143], v[182:185], v[96:99]
	v_mfma_f32_16x16x32_bf16 v[92:95], v[186:189], v[144:147], 0
	v_mfma_f32_16x16x32_bf16 v[88:91], v[194:197], v[144:147], 0
	v_mfma_f32_16x16x32_bf16 v[84:87], v[186:189], v[162:165], 0
	v_mfma_f32_16x16x32_bf16 v[80:83], v[194:197], v[162:165], 0
	v_mfma_f32_16x16x32_bf16 v[76:79], v[186:189], v[170:173], 0
	v_mfma_f32_16x16x32_bf16 v[72:75], v[194:197], v[170:173], 0
	v_mfma_f32_16x16x32_bf16 v[68:71], v[186:189], v[178:181], 0
	v_mfma_f32_16x16x32_bf16 v[64:67], v[194:197], v[178:181], 0
	v_mfma_f32_16x16x32_bf16 v[92:95], v[190:193], v[148:151], v[92:95]
	v_mfma_f32_16x16x32_bf16 v[88:91], v[198:201], v[148:151], v[88:91]
	v_mfma_f32_16x16x32_bf16 v[84:87], v[190:193], v[166:169], v[84:87]
	v_mfma_f32_16x16x32_bf16 v[80:83], v[198:201], v[166:169], v[80:83]
	v_mfma_f32_16x16x32_bf16 v[76:79], v[190:193], v[174:177], v[76:79]
	v_mfma_f32_16x16x32_bf16 v[72:75], v[198:201], v[174:177], v[72:75]
	v_mfma_f32_16x16x32_bf16 v[68:71], v[190:193], v[182:185], v[68:71]
	s_setprio 0
	v_mfma_f32_16x16x32_bf16 v[64:67], v[198:201], v[182:185], v[64:67]
	s_barrier
	s_mov_b32 m0, s55
	v_lshl_add_u64 v[202:203], s[24:25], 0, v[152:153]
	global_load_lds_dwordx4 v[202:203], off
	s_add_i32 m0, s55, 0x2000
	v_lshl_add_u64 v[202:203], s[24:25], 0, v[156:157]
	global_load_lds_dwordx4 v[202:203], off
	s_mov_b32 m0, s33
	v_lshl_add_u64 v[202:203], s[26:27], 0, v[152:153]
	global_load_lds_dwordx4 v[202:203], off
	s_mov_b32 m0, s34
	v_lshl_add_u64 v[202:203], s[26:27], 0, v[156:157]
	global_load_lds_dwordx4 v[202:203], off
	s_add_u32 s56, s24, s52
	s_addc_u32 s57, s25, 0
	s_add_i32 s55, s58, s31
	s_mov_b32 m0, s55
	v_lshl_add_u64 v[202:203], s[56:57], 0, v[152:153]
	global_load_lds_dwordx4 v[202:203], off
	s_add_i32 m0, s55, 0x2000
	v_lshl_add_u64 v[202:203], s[56:57], 0, v[156:157]
	global_load_lds_dwordx4 v[202:203], off
	ds_read_b128 v[144:147], v209 offset:16384
	ds_read_b128 v[162:165], v209 offset:18432
	ds_read_b128 v[170:173], v209 offset:20480
	ds_read_b128 v[178:181], v209 offset:22528
	ds_read_b128 v[148:151], v209 offset:17408
	ds_read_b128 v[166:169], v209 offset:19456
	ds_read_b128 v[174:177], v209 offset:21504
	ds_read_b128 v[182:185], v209 offset:23552
	s_waitcnt vmcnt(6)
	s_waitcnt lgkmcnt(0)
	s_barrier
; #define PG8_STAGE(bufoff, gbase, voff) do { _Pragma("unroll") for (int _i = 0; _i < 2; ++_i) \
;         __builtin_amdgcn_global_load_lds((const unsigned*)((const char*)(gbase) + (voff)[_i]), (LAS unsigned*)(lds + (bufoff) + ldsw + _i * 8192), 16, 0, 0); } while (0)
; #define PG8_LDA(dst, b, h) do { _Pragma("unroll") for (int m = 0; m < 4; ++m) _Pragma("unroll") for (int k = 0; k < 2; ++k) dst[m][k] = *(const LAS bf16x8*)(lds + PG8_SA(b, h) + aoff + m * 2048 + k * 1024); } while (0)
; #define PG8_LDB(dst, b, h) do { _Pragma("unroll") for (int n = 0; n < 2; ++n) _Pragma("unroll") for (int k = 0; k < 2; ++k) dst[n][k] = *(const LAS bf16x8*)(lds + PG8_SB(b, h) + boff + n * 2048 + k * 1024); } while (0)
; #define PG8_MMA(ai, bj, At, Bt) do { __builtin_amdgcn_s_setprio(1); _Pragma("unroll") for (int m = 0; m < 4; ++m) _Pragma("unroll") for (int n = 0; n < 2; ++n) _Pragma("unroll") for (int k = 0; k < 2; ++k) \
;         acc[ai][bj][m][n] = __builtin_amdgcn_mfma_f32_16x16x32_bf16(Bt[n][k], At[m][k], acc[ai][bj][m][n], 0, 0, 0); __builtin_amdgcn_s_setprio(0); } while (0)
; #define PG8_WAIT_V(n) asm volatile("s_waitcnt vmcnt(" #n ")" ::: "memory")
; #define PG8_WAIT_L(n) asm volatile("s_waitcnt lgkmcnt(" #n ")" ::: "memory")
; #define PG8_BAR __builtin_amdgcn_s_barrier()
; #define PG8_SCHED __builtin_amdgcn_sched_barrier(0)
; template <class Epi>
; __device__ __forceinline__ void gemm_phase(LAS unsigned char* lds, const Gemm g, const StaticOrder& S, const Epi& E) {
;     ...
;             PG8_BAR; PG8_WAIT_L(0); PG8_MMA(1, 0, At, B0); PG8_BAR; PG8_SCHED;
;             PG8_STAGE(PG8_SB(0, 1), b2 + hstepB, voffB);
;             PG8_WAIT_V(6); PG8_BAR; PG8_MMA(1, 1, At, B1); PG8_BAR;
;             PG8_LDB(B0, 1, 0); PG8_SCHED; PG8_LDA(At, 1, 0); PG8_STAGE(PG8_SA(0, 1), a2 + hstepA, voffA);
;             PG8_WAIT_L(8); PG8_BAR; PG8_WAIT_L(0); PG8_MMA(0, 0, At, B0); PG8_BAR; PG8_SCHED;
;             PG8_LDB(B1, 1, 1); PG8_STAGE(PG8_SB(1, 0), b3, voffB);
;             PG8_BAR; PG8_WAIT_L(0); PG8_MMA(0, 1, At, B1); PG8_BAR;
	v_mfma_f32_16x16x32_bf16 v[60:63], v[128:131], v[144:147], 0
	s_setprio 1
	v_mfma_f32_16x16x32_bf16 v[56:59], v[136:139], v[144:147], 0
	v_mfma_f32_16x16x32_bf16 v[52:55], v[128:131], v[162:165], 0
	v_mfma_f32_16x16x32_bf16 v[48:51], v[136:139], v[162:165], 0
	v_mfma_f32_16x16x32_bf16 v[44:47], v[128:131], v[170:173], 0
	v_mfma_f32_16x16x32_bf16 v[40:43], v[136:139], v[170:173], 0
	v_mfma_f32_16x16x32_bf16 v[36:39], v[128:131], v[178:181], 0
	v_mfma_f32_16x16x32_bf16 v[32:35], v[136:139], v[178:181], 0
	v_mfma_f32_16x16x32_bf16 v[60:63], v[132:135], v[148:151], v[60:63]
	v_mfma_f32_16x16x32_bf16 v[56:59], v[140:143], v[148:151], v[56:59]
	v_mfma_f32_16x16x32_bf16 v[52:55], v[132:135], v[166:169], v[52:55]
	v_mfma_f32_16x16x32_bf16 v[48:51], v[140:143], v[166:169], v[48:51]
	v_mfma_f32_16x16x32_bf16 v[44:47], v[132:135], v[174:177], v[44:47]
	v_mfma_f32_16x16x32_bf16 v[40:43], v[140:143], v[174:177], v[40:43]
	v_mfma_f32_16x16x32_bf16 v[36:39], v[132:135], v[182:185], v[36:39]
	v_mfma_f32_16x16x32_bf16 v[32:35], v[140:143], v[182:185], v[32:35]
	v_mfma_f32_16x16x32_bf16 v[28:31], v[186:189], v[144:147], 0
	v_mfma_f32_16x16x32_bf16 v[24:27], v[194:197], v[144:147], 0
	s_add_i32 s55, 0, 0x18000
	v_add_u32_e32 v140, s55, v207
	v_mfma_f32_16x16x32_bf16 v[20:23], v[186:189], v[162:165], 0
	v_mfma_f32_16x16x32_bf16 v[16:19], v[194:197], v[162:165], 0
	v_mfma_f32_16x16x32_bf16 v[12:15], v[186:189], v[170:173], 0
	v_mfma_f32_16x16x32_bf16 v[8:11], v[194:197], v[170:173], 0
	v_mfma_f32_16x16x32_bf16 v[4:7], v[186:189], v[178:181], 0
	v_mfma_f32_16x16x32_bf16 v[0:3], v[194:197], v[178:181], 0
	v_mfma_f32_16x16x32_bf16 v[28:31], v[190:193], v[148:151], v[28:31]
	v_mfma_f32_16x16x32_bf16 v[24:27], v[198:201], v[148:151], v[24:27]
	v_mfma_f32_16x16x32_bf16 v[20:23], v[190:193], v[166:169], v[20:23]
	v_mfma_f32_16x16x32_bf16 v[16:19], v[198:201], v[166:169], v[16:19]
	v_mfma_f32_16x16x32_bf16 v[12:15], v[190:193], v[174:177], v[12:15]
	v_mfma_f32_16x16x32_bf16 v[8:11], v[198:201], v[174:177], v[8:11]
	v_mfma_f32_16x16x32_bf16 v[4:7], v[190:193], v[182:185], v[4:7]
	s_setprio 0
	v_mfma_f32_16x16x32_bf16 v[0:3], v[198:201], v[182:185], v[0:3]
	s_barrier
	s_add_u32 s26, s26, s52
	s_addc_u32 s27, s27, 0
	s_mov_b32 m0, s35
	v_lshl_add_u64 v[186:187], s[26:27], 0, v[152:153]
	global_load_lds_dwordx4 v[186:187], off
	s_mov_b32 m0, s36
	v_lshl_add_u64 v[186:187], s[26:27], 0, v[156:157]
	global_load_lds_dwordx4 v[186:187], off
	ds_read_b128 v[128:131], v140
	ds_read_b128 v[136:139], v140 offset:2048
	ds_read_b128 v[132:135], v140 offset:1024
	ds_read_b128 v[140:143], v140 offset:3072
	ds_read_b128 v[144:147], v209 offset:32768
	ds_read_b128 v[162:165], v209 offset:34816
	ds_read_b128 v[170:173], v209 offset:36864
	ds_read_b128 v[178:181], v209 offset:38912
	ds_read_b128 v[148:151], v209 offset:33792
	ds_read_b128 v[166:169], v209 offset:35840
	ds_read_b128 v[174:177], v209 offset:37888
	ds_read_b128 v[182:185], v209 offset:39936
	s_mov_b32 s26, 0x1c000
	s_add_u32 s24, s24, 0x4000
	s_addc_u32 s25, s25, 0
	s_add_i32 s27, s55, s31
	v_add_u32_e32 v198, s26, v207
	ds_read_b128 v[186:189], v198
	ds_read_b128 v[194:197], v198 offset:2048
	ds_read_b128 v[190:193], v198 offset:1024
	ds_read_b128 v[198:201], v198 offset:3072
	s_waitcnt lgkmcnt(0)
	s_barrier
	v_mfma_f32_16x16x32_bf16 v[124:127], v[128:131], v[144:147], v[124:127]
	s_setprio 1
	v_mfma_f32_16x16x32_bf16 v[120:123], v[136:139], v[144:147], v[120:123]
	v_mfma_f32_16x16x32_bf16 v[116:119], v[128:131], v[162:165], v[116:119]
	v_mfma_f32_16x16x32_bf16 v[112:115], v[136:139], v[162:165], v[112:115]
	v_mfma_f32_16x16x32_bf16 v[108:111], v[128:131], v[170:173], v[108:111]
	v_mfma_f32_16x16x32_bf16 v[104:107], v[136:139], v[170:173], v[104:107]
	v_mfma_f32_16x16x32_bf16 v[100:103], v[128:131], v[178:181], v[100:103]
	v_mfma_f32_16x16x32_bf16 v[96:99], v[136:139], v[178:181], v[96:99]
	v_mfma_f32_16x16x32_bf16 v[124:127], v[132:135], v[148:151], v[124:127]
	v_mfma_f32_16x16x32_bf16 v[120:123], v[140:143], v[148:151], v[120:123]
	v_mfma_f32_16x16x32_bf16 v[116:119], v[132:135], v[166:169], v[116:119]
	v_mfma_f32_16x16x32_bf16 v[112:115], v[140:143], v[166:169], v[112:115]
	v_mfma_f32_16x16x32_bf16 v[108:111], v[132:135], v[174:177], v[108:111]
	v_mfma_f32_16x16x32_bf16 v[104:107], v[140:143], v[174:177], v[104:107]
	v_mfma_f32_16x16x32_bf16 v[100:103], v[132:135], v[182:185], v[100:103]
	v_mfma_f32_16x16x32_bf16 v[96:99], v[140:143], v[182:185], v[96:99]
	v_mfma_f32_16x16x32_bf16 v[92:95], v[186:189], v[144:147], v[92:95]
	v_mfma_f32_16x16x32_bf16 v[88:91], v[194:197], v[144:147], v[88:91]
	v_mfma_f32_16x16x32_bf16 v[84:87], v[186:189], v[162:165], v[84:87]
	v_mfma_f32_16x16x32_bf16 v[80:83], v[194:197], v[162:165], v[80:83]
	v_mfma_f32_16x16x32_bf16 v[76:79], v[186:189], v[170:173], v[76:79]
	v_mfma_f32_16x16x32_bf16 v[72:75], v[194:197], v[170:173], v[72:75]
	v_mfma_f32_16x16x32_bf16 v[68:71], v[186:189], v[178:181], v[68:71]
	v_mfma_f32_16x16x32_bf16 v[64:67], v[194:197], v[178:181], v[64:67]
	v_mfma_f32_16x16x32_bf16 v[92:95], v[190:193], v[148:151], v[92:95]
	v_mfma_f32_16x16x32_bf16 v[88:91], v[198:201], v[148:151], v[88:91]
	v_mfma_f32_16x16x32_bf16 v[84:87], v[190:193], v[166:169], v[84:87]
	v_mfma_f32_16x16x32_bf16 v[80:83], v[198:201], v[166:169], v[80:83]
	v_mfma_f32_16x16x32_bf16 v[76:79], v[190:193], v[174:177], v[76:79]
	v_mfma_f32_16x16x32_bf16 v[72:75], v[198:201], v[174:177], v[72:75]
	v_mfma_f32_16x16x32_bf16 v[68:71], v[190:193], v[182:185], v[68:71]
	s_setprio 0
	v_mfma_f32_16x16x32_bf16 v[64:67], v[198:201], v[182:185], v[64:67]
	s_barrier
; #define PG8_STAGE(bufoff, gbase, voff) do { _Pragma("unroll") for (int _i = 0; _i < 2; ++_i) \
;         __builtin_amdgcn_global_load_lds((const unsigned*)((const char*)(gbase) + (voff)[_i]), (LAS unsigned*)(lds + (bufoff) + ldsw + _i * 8192), 16, 0, 0); } while (0)
; #define PG8_LDA(dst, b, h) do { _Pragma("unroll") for (int m = 0; m < 4; ++m) _Pragma("unroll") for (int k = 0; k < 2; ++k) dst[m][k] = *(const LAS bf16x8*)(lds + PG8_SA(b, h) + aoff + m * 2048 + k * 1024); } while (0)
; #define PG8_LDB(dst, b, h) do { _Pragma("unroll") for (int n = 0; n < 2; ++n) _Pragma("unroll") for (int k = 0; k < 2; ++k) dst[n][k] = *(const LAS bf16x8*)(lds + PG8_SB(b, h) + boff + n * 2048 + k * 1024); } while (0)
; #define PG8_MMA(ai, bj, At, Bt) do { __builtin_amdgcn_s_setprio(1); _Pragma("unroll") for (int m = 0; m < 4; ++m) _Pragma("unroll") for (int n = 0; n < 2; ++n) _Pragma("unroll") for (int k = 0; k < 2; ++k) \
;         acc[ai][bj][m][n] = __builtin_amdgcn_mfma_f32_16x16x32_bf16(Bt[n][k], At[m][k], acc[ai][bj][m][n], 0, 0, 0); __builtin_amdgcn_s_setprio(0); } while (0)
; #define PG8_WAIT_V(n) asm volatile("s_waitcnt vmcnt(" #n ")" ::: "memory")
; #define PG8_WAIT_L(n) asm volatile("s_waitcnt lgkmcnt(" #n ")" ::: "memory")
; #define PG8_BAR __builtin_amdgcn_s_barrier()
; #define PG8_SCHED __builtin_amdgcn_sched_barrier(0)
; template <class Epi>
; __device__ __forceinline__ void gemm_phase(LAS unsigned char* lds, const Gemm g, const StaticOrder& S, const Epi& E) {
;     ...
;             const bool last = (t == nt - 2);
;             const char* a1 = cA + (size_t)(t + 1) * kstep;
;             const char* a2 = last ? nA : cA + (size_t)(t + 2) * kstep; const char* b2 = last ? nB : cB + (size_t)(t + 2) * kstep;
;             const char* a3 = a2 + kstep; const char* b3 = b2 + kstep;
;             PG8_LDB(B0, 0, 0); PG8_SCHED; PG8_LDA(At, 0, 0); PG8_STAGE(PG8_SA(1, 1), a1 + hstepA, voffA);
;             PG8_WAIT_L(8); PG8_BAR; PG8_WAIT_L(0); PG8_MMA(0, 0, At, B0); PG8_BAR; PG8_SCHED;
;             PG8_LDB(B1, 0, 1); PG8_STAGE(PG8_SB(0, 0), b2, voffB);
;     ...
;             PG8_LDA(At, 1, 1); PG8_STAGE(PG8_SA(1, 0), a3, voffA);
;             PG8_BAR; PG8_WAIT_L(0); PG8_MMA(1, 0, At, B0); PG8_BAR; PG8_SCHED;
;             PG8_STAGE(PG8_SB(1, 1), b3 + hstepB, voffB);
;             PG8_WAIT_V(6); PG8_BAR; PG8_MMA(1, 1, At, B1); PG8_BAR;
	s_mov_b32 m0, s27
	v_lshl_add_u64 v[202:203], s[24:25], 0, v[152:153]
	global_load_lds_dwordx4 v[202:203], off
	s_add_i32 m0, s27, 0x2000
	v_lshl_add_u64 v[202:203], s[24:25], 0, v[156:157]
	global_load_lds_dwordx4 v[202:203], off
	s_mov_b32 m0, s38
	v_lshl_add_u64 v[202:203], s[22:23], 0, v[152:153]
	global_load_lds_dwordx4 v[202:203], off
	s_mov_b32 m0, s39
	v_lshl_add_u64 v[202:203], s[22:23], 0, v[156:157]
	global_load_lds_dwordx4 v[202:203], off
	s_add_u32 s22, s24, s52
	s_addc_u32 s23, s25, 0
	s_add_i32 s24, s26, s31
	s_mov_b32 m0, s24
	v_lshl_add_u64 v[202:203], s[22:23], 0, v[152:153]
	global_load_lds_dwordx4 v[202:203], off
	s_add_i32 m0, s24, 0x2000
	v_lshl_add_u64 v[202:203], s[22:23], 0, v[156:157]
	global_load_lds_dwordx4 v[202:203], off
	ds_read_b128 v[144:147], v209 offset:49152
	ds_read_b128 v[162:165], v209 offset:51200
	ds_read_b128 v[170:173], v209 offset:53248
	ds_read_b128 v[178:181], v209 offset:55296
	ds_read_b128 v[148:151], v209 offset:50176
	ds_read_b128 v[166:169], v209 offset:52224
	ds_read_b128 v[174:177], v209 offset:54272
	ds_read_b128 v[182:185], v209 offset:56320
	s_waitcnt vmcnt(6)
	s_waitcnt lgkmcnt(0)
	s_barrier
	v_mfma_f32_16x16x32_bf16 v[60:63], v[128:131], v[144:147], v[60:63]
	s_setprio 1
	v_mfma_f32_16x16x32_bf16 v[56:59], v[136:139], v[144:147], v[56:59]
	v_mfma_f32_16x16x32_bf16 v[52:55], v[128:131], v[162:165], v[52:55]
	v_mfma_f32_16x16x32_bf16 v[48:51], v[136:139], v[162:165], v[48:51]
	v_mfma_f32_16x16x32_bf16 v[44:47], v[128:131], v[170:173], v[44:47]
	v_mfma_f32_16x16x32_bf16 v[40:43], v[136:139], v[170:173], v[40:43]
	v_mfma_f32_16x16x32_bf16 v[36:39], v[128:131], v[178:181], v[36:39]
	v_mfma_f32_16x16x32_bf16 v[32:35], v[136:139], v[178:181], v[32:35]
	v_mfma_f32_16x16x32_bf16 v[60:63], v[132:135], v[148:151], v[60:63]
	v_mfma_f32_16x16x32_bf16 v[56:59], v[140:143], v[148:151], v[56:59]
	v_mfma_f32_16x16x32_bf16 v[52:55], v[132:135], v[166:169], v[52:55]
	v_mfma_f32_16x16x32_bf16 v[48:51], v[140:143], v[166:169], v[48:51]
	v_mfma_f32_16x16x32_bf16 v[44:47], v[132:135], v[174:177], v[44:47]
	v_mfma_f32_16x16x32_bf16 v[40:43], v[140:143], v[174:177], v[40:43]
	v_mfma_f32_16x16x32_bf16 v[36:39], v[132:135], v[182:185], v[36:39]
	v_mfma_f32_16x16x32_bf16 v[32:35], v[140:143], v[182:185], v[32:35]
	v_mfma_f32_16x16x32_bf16 v[28:31], v[186:189], v[144:147], v[28:31]
	v_mfma_f32_16x16x32_bf16 v[24:27], v[194:197], v[144:147], v[24:27]
	s_add_u32 s4, s4, 0x8000
	s_addc_u32 s5, s5, 0
	s_add_u32 s50, s50, 0x8000
	s_addc_u32 s51, s51, 0
	v_mfma_f32_16x16x32_bf16 v[20:23], v[186:189], v[162:165], v[20:23]
	v_mfma_f32_16x16x32_bf16 v[16:19], v[194:197], v[162:165], v[16:19]
	v_mfma_f32_16x16x32_bf16 v[12:15], v[186:189], v[170:173], v[12:15]
	v_mfma_f32_16x16x32_bf16 v[8:11], v[194:197], v[170:173], v[8:11]
	v_mfma_f32_16x16x32_bf16 v[4:7], v[186:189], v[178:181], v[4:7]
	v_mfma_f32_16x16x32_bf16 v[0:3], v[194:197], v[178:181], v[0:3]
	v_mfma_f32_16x16x32_bf16 v[28:31], v[190:193], v[148:151], v[28:31]
	v_mfma_f32_16x16x32_bf16 v[24:27], v[198:201], v[148:151], v[24:27]
	v_mfma_f32_16x16x32_bf16 v[20:23], v[190:193], v[166:169], v[20:23]
	v_mfma_f32_16x16x32_bf16 v[16:19], v[198:201], v[166:169], v[16:19]
	v_mfma_f32_16x16x32_bf16 v[12:15], v[190:193], v[174:177], v[12:15]
	v_mfma_f32_16x16x32_bf16 v[8:11], v[198:201], v[174:177], v[8:11]
	v_mfma_f32_16x16x32_bf16 v[4:7], v[190:193], v[182:185], v[4:7]
	s_cmp_ge_u32 s54, s28
	s_mov_b32 s22, s54
	s_setprio 0
	v_mfma_f32_16x16x32_bf16 v[0:3], v[198:201], v[182:185], v[0:3]
	s_barrier
	s_cbranch_scc0 .LBB0_187
	s_branch .Lpeel_done_187
.LBB0_187:
	s_add_i32 s54, s22, 2
	s_add_u32 s23, s4, 0x4000
	s_addc_u32 s24, s5, 0
	s_cmp_eq_u32 s40, s22
	s_cselect_b32 s26, s6, s23
	s_cselect_b32 s27, s7, s24
	s_cselect_b32 s24, s20, s50
	s_cselect_b32 s25, s21, s51
	s_add_u32 s22, s26, 0x4000
	s_addc_u32 s23, s27, 0
	s_add_i32 m0, s33, 0xc000
	v_lshl_add_u64 v[186:187], s[4:5], 0, v[158:159]
	global_load_lds_dwordx4 v[186:187], off
	s_add_i32 m0, s33, 0xe000
	v_lshl_add_u64 v[186:187], s[4:5], 0, v[160:161]
	global_load_lds_dwordx4 v[186:187], off
	s_mov_b32 s55, 0x10000
	v_add_u32_e32 v140, s55, v207
	ds_read_b128 v[128:131], v140
	ds_read_b128 v[136:139], v140 offset:2048
	ds_read_b128 v[132:135], v140 offset:1024
	ds_read_b128 v[140:143], v140 offset:3072
	ds_read_b128 v[144:147], v209
	ds_read_b128 v[162:165], v209 offset:2048
	ds_read_b128 v[170:173], v209 offset:4096
	ds_read_b128 v[178:181], v209 offset:6144
	ds_read_b128 v[148:151], v209 offset:1024
	ds_read_b128 v[166:169], v209 offset:3072
	ds_read_b128 v[174:177], v209 offset:5120
	ds_read_b128 v[182:185], v209 offset:7168
	s_mov_b32 s58, 0x14000
	s_add_i32 s55, s55, s31
	v_add_u32_e32 v198, s58, v207
	ds_read_b128 v[186:189], v198
	ds_read_b128 v[194:197], v198 offset:2048
	ds_read_b128 v[190:193], v198 offset:1024
	ds_read_b128 v[198:201], v198 offset:3072
	s_waitcnt lgkmcnt(0)
	s_barrier
; #define PG8_STAGE(bufoff, gbase, voff) do { _Pragma("unroll") for (int _i = 0; _i < 2; ++_i) \
;         __builtin_amdgcn_global_load_lds((const unsigned*)((const char*)(gbase) + (voff)[_i]), (LAS unsigned*)(lds + (bufoff) + ldsw + _i * 8192), 16, 0, 0); } while (0)
; #define PG8_LDA(dst, b, h) do { _Pragma("unroll") for (int m = 0; m < 4; ++m) _Pragma("unroll") for (int k = 0; k < 2; ++k) dst[m][k] = *(const LAS bf16x8*)(lds + PG8_SA(b, h) + aoff + m * 2048 + k * 1024); } while (0)
; #define PG8_LDB(dst, b, h) do { _Pragma("unroll") for (int n = 0; n < 2; ++n) _Pragma("unroll") for (int k = 0; k < 2; ++k) dst[n][k] = *(const LAS bf16x8*)(lds + PG8_SB(b, h) + boff + n * 2048 + k * 1024); } while (0)
; #define PG8_MMA(ai, bj, At, Bt) do { __builtin_amdgcn_s_setprio(1); _Pragma("unroll") for (int m = 0; m < 4; ++m) _Pragma("unroll") for (int n = 0; n < 2; ++n) _Pragma("unroll") for (int k = 0; k < 2; ++k) \
;         acc[ai][bj][m][n] = __builtin_amdgcn_mfma_f32_16x16x32_bf16(Bt[n][k], At[m][k], acc[ai][bj][m][n], 0, 0, 0); __builtin_amdgcn_s_setprio(0); } while (0)
; #define PG8_WAIT_V(n) asm volatile("s_waitcnt vmcnt(" #n ")" ::: "memory")
; #define PG8_WAIT_L(n) asm volatile("s_waitcnt lgkmcnt(" #n ")" ::: "memory")
; #define PG8_BAR __builtin_amdgcn_s_barrier()
; #define PG8_SCHED __builtin_amdgcn_sched_barrier(0)
; template <class Epi>
; __device__ __forceinline__ void gemm_phase(LAS unsigned char* lds, const Gemm g, const StaticOrder& S, const Epi& E) {
;     ...
;             PG8_WAIT_L(8); PG8_BAR; PG8_WAIT_L(0); PG8_MMA(0, 0, At, B0); PG8_BAR; PG8_SCHED;
;             PG8_LDB(B1, 0, 1); PG8_STAGE(PG8_SB(0, 0), b2, voffB);
;             PG8_BAR; PG8_WAIT_L(0); PG8_MMA(0, 1, At, B1); PG8_BAR;
;             PG8_LDA(At, 0, 1); PG8_STAGE(PG8_SA(0, 0), a2, voffA);
;             PG8_BAR; PG8_WAIT_L(0); PG8_MMA(1, 0, At, B0); PG8_BAR; PG8_SCHED;
;             PG8_STAGE(PG8_SB(0, 1), b2 + hstepB, voffB);
;             PG8_WAIT_V(6); PG8_BAR; PG8_MMA(1, 1, At, B1); PG8_BAR;
	v_mfma_f32_16x16x32_bf16 v[124:127], v[128:131], v[144:147], v[124:127]
	s_setprio 1
	v_mfma_f32_16x16x32_bf16 v[120:123], v[136:139], v[144:147], v[120:123]
	v_mfma_f32_16x16x32_bf16 v[116:119], v[128:131], v[162:165], v[116:119]
	v_mfma_f32_16x16x32_bf16 v[112:115], v[136:139], v[162:165], v[112:115]
	v_mfma_f32_16x16x32_bf16 v[108:111], v[128:131], v[170:173], v[108:111]
	v_mfma_f32_16x16x32_bf16 v[104:107], v[136:139], v[170:173], v[104:107]
	v_mfma_f32_16x16x32_bf16 v[100:103], v[128:131], v[178:181], v[100:103]
	v_mfma_f32_16x16x32_bf16 v[96:99], v[136:139], v[178:181], v[96:99]
	v_mfma_f32_16x16x32_bf16 v[124:127], v[132:135], v[148:151], v[124:127]
	v_mfma_f32_16x16x32_bf16 v[120:123], v[140:143], v[148:151], v[120:123]
	v_mfma_f32_16x16x32_bf16 v[116:119], v[132:135], v[166:169], v[116:119]
	v_mfma_f32_16x16x32_bf16 v[112:115], v[140:143], v[166:169], v[112:115]
	v_mfma_f32_16x16x32_bf16 v[108:111], v[132:135], v[174:177], v[108:111]
	v_mfma_f32_16x16x32_bf16 v[104:107], v[140:143], v[174:177], v[104:107]
	v_mfma_f32_16x16x32_bf16 v[100:103], v[132:135], v[182:185], v[100:103]
	v_mfma_f32_16x16x32_bf16 v[96:99], v[140:143], v[182:185], v[96:99]
	v_mfma_f32_16x16x32_bf16 v[92:95], v[186:189], v[144:147], v[92:95]
	v_mfma_f32_16x16x32_bf16 v[88:91], v[194:197], v[144:147], v[88:91]
	v_mfma_f32_16x16x32_bf16 v[84:87], v[186:189], v[162:165], v[84:87]
	v_mfma_f32_16x16x32_bf16 v[80:83], v[194:197], v[162:165], v[80:83]
	v_mfma_f32_16x16x32_bf16 v[76:79], v[186:189], v[170:173], v[76:79]
	v_mfma_f32_16x16x32_bf16 v[72:75], v[194:197], v[170:173], v[72:75]
	v_mfma_f32_16x16x32_bf16 v[68:71], v[186:189], v[178:181], v[68:71]
	v_mfma_f32_16x16x32_bf16 v[64:67], v[194:197], v[178:181], v[64:67]
	v_mfma_f32_16x16x32_bf16 v[92:95], v[190:193], v[148:151], v[92:95]
	v_mfma_f32_16x16x32_bf16 v[88:91], v[198:201], v[148:151], v[88:91]
	v_mfma_f32_16x16x32_bf16 v[84:87], v[190:193], v[166:169], v[84:87]
	v_mfma_f32_16x16x32_bf16 v[80:83], v[198:201], v[166:169], v[80:83]
	v_mfma_f32_16x16x32_bf16 v[76:79], v[190:193], v[174:177], v[76:79]
	v_mfma_f32_16x16x32_bf16 v[72:75], v[198:201], v[174:177], v[72:75]
	v_mfma_f32_16x16x32_bf16 v[68:71], v[190:193], v[182:185], v[68:71]
	s_setprio 0
	v_mfma_f32_16x16x32_bf16 v[64:67], v[198:201], v[182:185], v[64:67]
	s_barrier
	s_mov_b32 m0, s55
	v_lshl_add_u64 v[202:203], s[24:25], 0, v[152:153]
	global_load_lds_dwordx4 v[202:203], off
	s_add_i32 m0, s55, 0x2000
	v_lshl_add_u64 v[202:203], s[24:25], 0, v[156:157]
	global_load_lds_dwordx4 v[202:203], off
	s_mov_b32 m0, s33
	v_lshl_add_u64 v[202:203], s[26:27], 0, v[152:153]
	global_load_lds_dwordx4 v[202:203], off
	s_mov_b32 m0, s34
	v_lshl_add_u64 v[202:203], s[26:27], 0, v[156:157]
	global_load_lds_dwordx4 v[202:203], off
	s_add_u32 s56, s24, s52
	s_addc_u32 s57, s25, 0
	s_add_i32 s55, s58, s31
	s_mov_b32 m0, s55
	v_lshl_add_u64 v[202:203], s[56:57], 0, v[152:153]
	global_load_lds_dwordx4 v[202:203], off
	s_add_i32 m0, s55, 0x2000
	v_lshl_add_u64 v[202:203], s[56:57], 0, v[156:157]
	global_load_lds_dwordx4 v[202:203], off
	ds_read_b128 v[144:147], v209 offset:16384
	ds_read_b128 v[162:165], v209 offset:18432
	ds_read_b128 v[170:173], v209 offset:20480
	ds_read_b128 v[178:181], v209 offset:22528
	ds_read_b128 v[148:151], v209 offset:17408
	ds_read_b128 v[166:169], v209 offset:19456
	ds_read_b128 v[174:177], v209 offset:21504
	ds_read_b128 v[182:185], v209 offset:23552
	s_waitcnt vmcnt(6)
	s_waitcnt lgkmcnt(0)
	s_barrier
	v_mfma_f32_16x16x32_bf16 v[60:63], v[128:131], v[144:147], v[60:63]
	s_setprio 1
	v_mfma_f32_16x16x32_bf16 v[56:59], v[136:139], v[144:147], v[56:59]
	v_mfma_f32_16x16x32_bf16 v[52:55], v[128:131], v[162:165], v[52:55]
	v_mfma_f32_16x16x32_bf16 v[48:51], v[136:139], v[162:165], v[48:51]
	v_mfma_f32_16x16x32_bf16 v[44:47], v[128:131], v[170:173], v[44:47]
	v_mfma_f32_16x16x32_bf16 v[40:43], v[136:139], v[170:173], v[40:43]
	v_mfma_f32_16x16x32_bf16 v[36:39], v[128:131], v[178:181], v[36:39]
	v_mfma_f32_16x16x32_bf16 v[32:35], v[136:139], v[178:181], v[32:35]
	v_mfma_f32_16x16x32_bf16 v[60:63], v[132:135], v[148:151], v[60:63]
	v_mfma_f32_16x16x32_bf16 v[56:59], v[140:143], v[148:151], v[56:59]
	v_mfma_f32_16x16x32_bf16 v[52:55], v[132:135], v[166:169], v[52:55]
	v_mfma_f32_16x16x32_bf16 v[48:51], v[140:143], v[166:169], v[48:51]
	v_mfma_f32_16x16x32_bf16 v[44:47], v[132:135], v[174:177], v[44:47]
	v_mfma_f32_16x16x32_bf16 v[40:43], v[140:143], v[174:177], v[40:43]
	v_mfma_f32_16x16x32_bf16 v[36:39], v[132:135], v[182:185], v[36:39]
	v_mfma_f32_16x16x32_bf16 v[32:35], v[140:143], v[182:185], v[32:35]
	v_mfma_f32_16x16x32_bf16 v[28:31], v[186:189], v[144:147], v[28:31]
	v_mfma_f32_16x16x32_bf16 v[24:27], v[194:197], v[144:147], v[24:27]
	s_add_i32 s55, 0, 0x18000
	v_add_u32_e32 v140, s55, v207
	v_mfma_f32_16x16x32_bf16 v[20:23], v[186:189], v[162:165], v[20:23]
	v_mfma_f32_16x16x32_bf16 v[16:19], v[194:197], v[162:165], v[16:19]
	v_mfma_f32_16x16x32_bf16 v[12:15], v[186:189], v[170:173], v[12:15]
	v_mfma_f32_16x16x32_bf16 v[8:11], v[194:197], v[170:173], v[8:11]
	v_mfma_f32_16x16x32_bf16 v[4:7], v[186:189], v[178:181], v[4:7]
	v_mfma_f32_16x16x32_bf16 v[0:3], v[194:197], v[178:181], v[0:3]
	v_mfma_f32_16x16x32_bf16 v[28:31], v[190:193], v[148:151], v[28:31]
	v_mfma_f32_16x16x32_bf16 v[24:27], v[198:201], v[148:151], v[24:27]
	v_mfma_f32_16x16x32_bf16 v[20:23], v[190:193], v[166:169], v[20:23]
	v_mfma_f32_16x16x32_bf16 v[16:19], v[198:201], v[166:169], v[16:19]
	v_mfma_f32_16x16x32_bf16 v[12:15], v[190:193], v[174:177], v[12:15]
	v_mfma_f32_16x16x32_bf16 v[8:11], v[198:201], v[174:177], v[8:11]
	v_mfma_f32_16x16x32_bf16 v[4:7], v[190:193], v[182:185], v[4:7]
	s_setprio 0
	v_mfma_f32_16x16x32_bf16 v[0:3], v[198:201], v[182:185], v[0:3]
	s_barrier
; #define PG8_STAGE(bufoff, gbase, voff) do { _Pragma("unroll") for (int _i = 0; _i < 2; ++_i) \
;         __builtin_amdgcn_global_load_lds((const unsigned*)((const char*)(gbase) + (voff)[_i]), (LAS unsigned*)(lds + (bufoff) + ldsw + _i * 8192), 16, 0, 0); } while (0)
; #define PG8_LDA(dst, b, h) do { _Pragma("unroll") for (int m = 0; m < 4; ++m) _Pragma("unroll") for (int k = 0; k < 2; ++k) dst[m][k] = *(const LAS bf16x8*)(lds + PG8_SA(b, h) + aoff + m * 2048 + k * 1024); } while (0)
; #define PG8_LDB(dst, b, h) do { _Pragma("unroll") for (int n = 0; n < 2; ++n) _Pragma("unroll") for (int k = 0; k < 2; ++k) dst[n][k] = *(const LAS bf16x8*)(lds + PG8_SB(b, h) + boff + n * 2048 + k * 1024); } while (0)
; #define PG8_MMA(ai, bj, At, Bt) do { __builtin_amdgcn_s_setprio(1); _Pragma("unroll") for (int m = 0; m < 4; ++m) _Pragma("unroll") for (int n = 0; n < 2; ++n) _Pragma("unroll") for (int k = 0; k < 2; ++k) \
;         acc[ai][bj][m][n] = __builtin_amdgcn_mfma_f32_16x16x32_bf16(Bt[n][k], At[m][k], acc[ai][bj][m][n], 0, 0, 0); __builtin_amdgcn_s_setprio(0); } while (0)
; #define PG8_WAIT_V(n) asm volatile("s_waitcnt vmcnt(" #n ")" ::: "memory")
; #define PG8_WAIT_L(n) asm volatile("s_waitcnt lgkmcnt(" #n ")" ::: "memory")
; #define PG8_BAR __builtin_amdgcn_s_barrier()
; #define PG8_SCHED __builtin_amdgcn_sched_barrier(0)
; template <class Epi>
; __device__ __forceinline__ void gemm_phase(LAS unsigned char* lds, const Gemm g, const StaticOrder& S, const Epi& E) {
;     ...
;             PG8_LDB(B0, 1, 0); PG8_SCHED; PG8_LDA(At, 1, 0); PG8_STAGE(PG8_SA(0, 1), a2 + hstepA, voffA);
;             PG8_WAIT_L(8); PG8_BAR; PG8_WAIT_L(0); PG8_MMA(0, 0, At, B0); PG8_BAR; PG8_SCHED;
;             PG8_LDB(B1, 1, 1); PG8_STAGE(PG8_SB(1, 0), b3, voffB);
;             PG8_BAR; PG8_WAIT_L(0); PG8_MMA(0, 1, At, B1); PG8_BAR;
;             PG8_LDA(At, 1, 1); PG8_STAGE(PG8_SA(1, 0), a3, voffA);
;             PG8_BAR; PG8_WAIT_L(0); PG8_MMA(1, 0, At, B0); PG8_BAR; PG8_SCHED;
;             PG8_STAGE(PG8_SB(1, 1), b3 + hstepB, voffB);
;             PG8_WAIT_V(6); PG8_BAR; PG8_MMA(1, 1, At, B1); PG8_BAR;
	s_add_u32 s26, s26, s52
	s_addc_u32 s27, s27, 0
	s_mov_b32 m0, s35
	v_lshl_add_u64 v[186:187], s[26:27], 0, v[152:153]
	global_load_lds_dwordx4 v[186:187], off
	s_mov_b32 m0, s36
	v_lshl_add_u64 v[186:187], s[26:27], 0, v[156:157]
	global_load_lds_dwordx4 v[186:187], off
	ds_read_b128 v[128:131], v140
	ds_read_b128 v[136:139], v140 offset:2048
	ds_read_b128 v[132:135], v140 offset:1024
	ds_read_b128 v[140:143], v140 offset:3072
	ds_read_b128 v[144:147], v209 offset:32768
	ds_read_b128 v[162:165], v209 offset:34816
	ds_read_b128 v[170:173], v209 offset:36864
	ds_read_b128 v[178:181], v209 offset:38912
	ds_read_b128 v[148:151], v209 offset:33792
	ds_read_b128 v[166:169], v209 offset:35840
	ds_read_b128 v[174:177], v209 offset:37888
	ds_read_b128 v[182:185], v209 offset:39936
	s_mov_b32 s26, 0x1c000
	s_add_u32 s24, s24, 0x4000
	s_addc_u32 s25, s25, 0
	s_add_i32 s27, s55, s31
	v_add_u32_e32 v198, s26, v207
	ds_read_b128 v[186:189], v198
	ds_read_b128 v[194:197], v198 offset:2048
	ds_read_b128 v[190:193], v198 offset:1024
	ds_read_b128 v[198:201], v198 offset:3072
	s_waitcnt lgkmcnt(0)
	s_barrier
	v_mfma_f32_16x16x32_bf16 v[124:127], v[128:131], v[144:147], v[124:127]
	s_setprio 1
	v_mfma_f32_16x16x32_bf16 v[120:123], v[136:139], v[144:147], v[120:123]
	v_mfma_f32_16x16x32_bf16 v[116:119], v[128:131], v[162:165], v[116:119]
	v_mfma_f32_16x16x32_bf16 v[112:115], v[136:139], v[162:165], v[112:115]
	v_mfma_f32_16x16x32_bf16 v[108:111], v[128:131], v[170:173], v[108:111]
	v_mfma_f32_16x16x32_bf16 v[104:107], v[136:139], v[170:173], v[104:107]
	v_mfma_f32_16x16x32_bf16 v[100:103], v[128:131], v[178:181], v[100:103]
	v_mfma_f32_16x16x32_bf16 v[96:99], v[136:139], v[178:181], v[96:99]
	v_mfma_f32_16x16x32_bf16 v[124:127], v[132:135], v[148:151], v[124:127]
	v_mfma_f32_16x16x32_bf16 v[120:123], v[140:143], v[148:151], v[120:123]
	v_mfma_f32_16x16x32_bf16 v[116:119], v[132:135], v[166:169], v[116:119]
	v_mfma_f32_16x16x32_bf16 v[112:115], v[140:143], v[166:169], v[112:115]
	v_mfma_f32_16x16x32_bf16 v[108:111], v[132:135], v[174:177], v[108:111]
	v_mfma_f32_16x16x32_bf16 v[104:107], v[140:143], v[174:177], v[104:107]
	v_mfma_f32_16x16x32_bf16 v[100:103], v[132:135], v[182:185], v[100:103]
	v_mfma_f32_16x16x32_bf16 v[96:99], v[140:143], v[182:185], v[96:99]
	v_mfma_f32_16x16x32_bf16 v[92:95], v[186:189], v[144:147], v[92:95]
	v_mfma_f32_16x16x32_bf16 v[88:91], v[194:197], v[144:147], v[88:91]
	v_mfma_f32_16x16x32_bf16 v[84:87], v[186:189], v[162:165], v[84:87]
	v_mfma_f32_16x16x32_bf16 v[80:83], v[194:197], v[162:165], v[80:83]
	v_mfma_f32_16x16x32_bf16 v[76:79], v[186:189], v[170:173], v[76:79]
	v_mfma_f32_16x16x32_bf16 v[72:75], v[194:197], v[170:173], v[72:75]
	v_mfma_f32_16x16x32_bf16 v[68:71], v[186:189], v[178:181], v[68:71]
	v_mfma_f32_16x16x32_bf16 v[64:67], v[194:197], v[178:181], v[64:67]
	v_mfma_f32_16x16x32_bf16 v[92:95], v[190:193], v[148:151], v[92:95]
	v_mfma_f32_16x16x32_bf16 v[88:91], v[198:201], v[148:151], v[88:91]
	v_mfma_f32_16x16x32_bf16 v[84:87], v[190:193], v[166:169], v[84:87]
	v_mfma_f32_16x16x32_bf16 v[80:83], v[198:201], v[166:169], v[80:83]
	v_mfma_f32_16x16x32_bf16 v[76:79], v[190:193], v[174:177], v[76:79]
	v_mfma_f32_16x16x32_bf16 v[72:75], v[198:201], v[174:177], v[72:75]
	v_mfma_f32_16x16x32_bf16 v[68:71], v[190:193], v[182:185], v[68:71]
	s_setprio 0
	v_mfma_f32_16x16x32_bf16 v[64:67], v[198:201], v[182:185], v[64:67]
	s_barrier
	s_mov_b32 m0, s27
	v_lshl_add_u64 v[202:203], s[24:25], 0, v[152:153]
	global_load_lds_dwordx4 v[202:203], off
	s_add_i32 m0, s27, 0x2000
	v_lshl_add_u64 v[202:203], s[24:25], 0, v[156:157]
	global_load_lds_dwordx4 v[202:203], off
	s_mov_b32 m0, s38
	v_lshl_add_u64 v[202:203], s[22:23], 0, v[152:153]
	global_load_lds_dwordx4 v[202:203], off
	s_mov_b32 m0, s39
	v_lshl_add_u64 v[202:203], s[22:23], 0, v[156:157]
	global_load_lds_dwordx4 v[202:203], off
	s_add_u32 s22, s24, s52
	s_addc_u32 s23, s25, 0
	s_add_i32 s24, s26, s31
	s_mov_b32 m0, s24
	v_lshl_add_u64 v[202:203], s[22:23], 0, v[152:153]
	global_load_lds_dwordx4 v[202:203], off
	s_add_i32 m0, s24, 0x2000
	v_lshl_add_u64 v[202:203], s[22:23], 0, v[156:157]
	global_load_lds_dwordx4 v[202:203], off
	ds_read_b128 v[144:147], v209 offset:49152
	ds_read_b128 v[162:165], v209 offset:51200
	ds_read_b128 v[170:173], v209 offset:53248
	ds_read_b128 v[178:181], v209 offset:55296
	ds_read_b128 v[148:151], v209 offset:50176
	ds_read_b128 v[166:169], v209 offset:52224
	ds_read_b128 v[174:177], v209 offset:54272
	ds_read_b128 v[182:185], v209 offset:56320
	s_waitcnt vmcnt(6)
	s_waitcnt lgkmcnt(0)
	s_barrier
	v_mfma_f32_16x16x32_bf16 v[60:63], v[128:131], v[144:147], v[60:63]
	s_setprio 1
	v_mfma_f32_16x16x32_bf16 v[56:59], v[136:139], v[144:147], v[56:59]
	v_mfma_f32_16x16x32_bf16 v[52:55], v[128:131], v[162:165], v[52:55]
	v_mfma_f32_16x16x32_bf16 v[48:51], v[136:139], v[162:165], v[48:51]
	v_mfma_f32_16x16x32_bf16 v[44:47], v[128:131], v[170:173], v[44:47]
	v_mfma_f32_16x16x32_bf16 v[40:43], v[136:139], v[170:173], v[40:43]
	v_mfma_f32_16x16x32_bf16 v[36:39], v[128:131], v[178:181], v[36:39]
	v_mfma_f32_16x16x32_bf16 v[32:35], v[136:139], v[178:181], v[32:35]
	v_mfma_f32_16x16x32_bf16 v[60:63], v[132:135], v[148:151], v[60:63]
	v_mfma_f32_16x16x32_bf16 v[56:59], v[140:143], v[148:151], v[56:59]
	v_mfma_f32_16x16x32_bf16 v[52:55], v[132:135], v[166:169], v[52:55]
	v_mfma_f32_16x16x32_bf16 v[48:51], v[140:143], v[166:169], v[48:51]
	v_mfma_f32_16x16x32_bf16 v[44:47], v[132:135], v[174:177], v[44:47]
	v_mfma_f32_16x16x32_bf16 v[40:43], v[140:143], v[174:177], v[40:43]
	v_mfma_f32_16x16x32_bf16 v[36:39], v[132:135], v[182:185], v[36:39]
	v_mfma_f32_16x16x32_bf16 v[32:35], v[140:143], v[182:185], v[32:35]
	v_mfma_f32_16x16x32_bf16 v[28:31], v[186:189], v[144:147], v[28:31]
	v_mfma_f32_16x16x32_bf16 v[24:27], v[194:197], v[144:147], v[24:27]
	s_add_u32 s4, s4, 0x8000
	s_addc_u32 s5, s5, 0
	s_add_u32 s50, s50, 0x8000
	s_addc_u32 s51, s51, 0
	v_mfma_f32_16x16x32_bf16 v[20:23], v[186:189], v[162:165], v[20:23]
	v_mfma_f32_16x16x32_bf16 v[16:19], v[194:197], v[162:165], v[16:19]
	v_mfma_f32_16x16x32_bf16 v[12:15], v[186:189], v[170:173], v[12:15]
	v_mfma_f32_16x16x32_bf16 v[8:11], v[194:197], v[170:173], v[8:11]
	v_mfma_f32_16x16x32_bf16 v[4:7], v[186:189], v[178:181], v[4:7]
	v_mfma_f32_16x16x32_bf16 v[0:3], v[194:197], v[178:181], v[0:3]
	v_mfma_f32_16x16x32_bf16 v[28:31], v[190:193], v[148:151], v[28:31]
	v_mfma_f32_16x16x32_bf16 v[24:27], v[198:201], v[148:151], v[24:27]
	v_mfma_f32_16x16x32_bf16 v[20:23], v[190:193], v[166:169], v[20:23]
	v_mfma_f32_16x16x32_bf16 v[16:19], v[198:201], v[166:169], v[16:19]
	v_mfma_f32_16x16x32_bf16 v[12:15], v[190:193], v[174:177], v[12:15]
	v_mfma_f32_16x16x32_bf16 v[8:11], v[198:201], v[174:177], v[8:11]
	v_mfma_f32_16x16x32_bf16 v[4:7], v[190:193], v[182:185], v[4:7]
	s_cmp_ge_u32 s54, s28
	s_mov_b32 s22, s54
	s_setprio 0
	v_mfma_f32_16x16x32_bf16 v[0:3], v[198:201], v[182:185], v[0:3]
	s_barrier
	s_cbranch_scc0 .LBB0_187

; #define PG8_STAGE(bufoff, gbase, voff) do { _Pragma("unroll") for (int _i = 0; _i < 2; ++_i) \
;         __builtin_amdgcn_global_load_lds((const unsigned*)((const char*)(gbase) + (voff)[_i]), (LAS unsigned*)(lds + (bufoff) + ldsw + _i * 8192), 16, 0, 0); } while (0)
; #define PG8_LDA(dst, b, h) do { _Pragma("unroll") for (int m = 0; m < 4; ++m) _Pragma("unroll") for (int k = 0; k < 2; ++k) dst[m][k] = *(const LAS bf16x8*)(lds + PG8_SA(b, h) + aoff + m * 2048 + k * 1024); } while (0)
; #define PG8_LDB(dst, b, h) do { _Pragma("unroll") for (int n = 0; n < 2; ++n) _Pragma("unroll") for (int k = 0; k < 2; ++k) dst[n][k] = *(const LAS bf16x8*)(lds + PG8_SB(b, h) + boff + n * 2048 + k * 1024); } while (0)
; #define PG8_WAIT_V(n) asm volatile("s_waitcnt vmcnt(" #n ")" ::: "memory")
; #define PG8_WAIT_L(n) asm volatile("s_waitcnt lgkmcnt(" #n ")" ::: "memory")
; #define PG8_BAR __builtin_amdgcn_s_barrier()
; #define PG8_SCHED __builtin_amdgcn_sched_barrier(0)
; template <class Epi>
; __device__ __forceinline__ void gemm_phase(LAS unsigned char* lds, const Gemm g, const StaticOrder& S, const Epi& E) {
;     ...
;         const bool has_next = S.next(ui + 1, nxt);
;         const char* nA = has_next ? (const char*)g.A + (size_t)nxt.pm * tstepA : cA; const char* nB = has_next ? (const char*)g.Bt + (size_t)nxt.pn * tstepB : cB;
;         for (int t = 0; t < nt; t += 2) {
;             const bool last = (t == nt - 2);
;             const char* a1 = cA + (size_t)(t + 1) * kstep;
;             const char* a2 = last ? nA : cA + (size_t)(t + 2) * kstep; const char* b2 = last ? nB : cB + (size_t)(t + 2) * kstep;
;             const char* a3 = a2 + kstep; const char* b3 = b2 + kstep;
;             PG8_LDB(B0, 0, 0); PG8_SCHED; PG8_LDA(At, 0, 0); PG8_STAGE(PG8_SA(1, 1), a1 + hstepA, voffA);
;             PG8_WAIT_L(8); PG8_BAR; PG8_WAIT_L(0); PG8_MMA(0, 0, At, B0); PG8_BAR; PG8_SCHED;
;             PG8_LDB(B1, 0, 1); PG8_STAGE(PG8_SB(0, 0), b2, voffB);
;             PG8_BAR; PG8_WAIT_L(0); PG8_MMA(0, 1, At, B1); PG8_BAR;
;             PG8_LDA(At, 0, 1); PG8_STAGE(PG8_SA(0, 0), a2, voffA);
;             PG8_BAR; PG8_WAIT_L(0); PG8_MMA(1, 0, At, B0); PG8_BAR; PG8_SCHED;
;             PG8_STAGE(PG8_SB(0, 1), b2 + hstepB, voffB);
;             PG8_WAIT_V(6); PG8_BAR; PG8_MMA(1, 1, At, B1); PG8_BAR;
.LBB0_246:
	s_ashr_i32 s5, s4, 31
	v_cmp_lt_i64_e32 vcc, s[6:7], v[154:155]
	s_lshl_b64 s[6:7], s[4:5], 20
	v_readlane_b32 s8, v252, 53
	v_readlane_b32 s9, v252, 54
	s_add_u32 s6, s8, s6
	s_addc_u32 s7, s9, s7
	s_and_b64 s[8:9], vcc, exec
	s_cselect_b32 s5, s7, s13
	s_cselect_b32 s11, s6, s12
	s_ashr_i32 s3, s2, 31
	s_lshl_b64 s[8:9], s[2:3], 20
	s_add_u32 s8, s21, s8
	s_addc_u32 s9, s22, s9
	s_and_b64 s[16:17], vcc, exec
	s_cselect_b32 s3, s9, s15
	s_cselect_b32 s35, s8, s14
	s_add_u32 s12, s12, 0x84000
	s_addc_u32 s13, s13, 0
	s_add_u32 s36, s14, 0x8000
	s_addc_u32 s37, s15, 0
	s_mov_b32 s38, -2
	s_add_u32 s14, s12, 0xfff84000
	s_addc_u32 s15, s13, -1
	s_cmp_eq_u32 s38, 28
	s_cselect_b32 s18, s11, s14
	s_cselect_b32 s19, s5, s15
	s_cselect_b32 s14, s35, s36
	s_cselect_b32 s15, s3, s37
	s_add_u32 s16, s18, 0x4000
	s_addc_u32 s17, s19, 0
	s_add_i32 m0, s25, 0xc000
	v_lshl_add_u64 v[194:195], s[12:13], 0, v[156:157]
	global_load_lds_dwordx4 v[194:195], off
	s_add_i32 m0, s25, 0xe000
	v_lshl_add_u64 v[194:195], s[12:13], 0, v[158:159]
	global_load_lds_dwordx4 v[194:195], off
	s_mov_b32 s39, 0x10000
	v_add_u32_e32 v140, s39, v170
	ds_read_b128 v[128:131], v140
	ds_read_b128 v[136:139], v140 offset:2048
	ds_read_b128 v[132:135], v140 offset:1024
	ds_read_b128 v[140:143], v140 offset:3072
	ds_read_b128 v[144:147], v172
	ds_read_b128 v[166:169], v172 offset:2048
	ds_read_b128 v[178:181], v172 offset:4096
	ds_read_b128 v[186:189], v172 offset:6144
	ds_read_b128 v[148:151], v172 offset:1024
	ds_read_b128 v[174:177], v172 offset:3072
	ds_read_b128 v[182:185], v172 offset:5120
	ds_read_b128 v[190:193], v172 offset:7168
	s_mov_b32 s42, 0x14000
	s_add_i32 s39, s39, s23
	v_add_u32_e32 v152, s42, v170
	ds_read_b128 v[194:197], v152
	ds_read_b128 v[202:205], v152 offset:2048
	ds_read_b128 v[198:201], v152 offset:1024
	ds_read_b128 v[206:209], v152 offset:3072
	s_waitcnt lgkmcnt(0)
	s_barrier
	v_mfma_f32_16x16x32_bf16 v[124:127], v[128:131], v[144:147], 0
	s_setprio 1
	v_mfma_f32_16x16x32_bf16 v[120:123], v[136:139], v[144:147], 0
	v_mfma_f32_16x16x32_bf16 v[108:111], v[128:131], v[166:169], 0
	v_mfma_f32_16x16x32_bf16 v[104:107], v[136:139], v[166:169], 0
	v_mfma_f32_16x16x32_bf16 v[92:95], v[128:131], v[178:181], 0
	v_mfma_f32_16x16x32_bf16 v[88:91], v[136:139], v[178:181], 0
	v_mfma_f32_16x16x32_bf16 v[76:79], v[128:131], v[186:189], 0
	v_mfma_f32_16x16x32_bf16 v[72:75], v[136:139], v[186:189], 0
	v_mfma_f32_16x16x32_bf16 v[124:127], v[132:135], v[148:151], v[124:127]
	v_mfma_f32_16x16x32_bf16 v[120:123], v[140:143], v[148:151], v[120:123]
	v_mfma_f32_16x16x32_bf16 v[108:111], v[132:135], v[174:177], v[108:111]
	v_mfma_f32_16x16x32_bf16 v[104:107], v[140:143], v[174:177], v[104:107]
	v_mfma_f32_16x16x32_bf16 v[92:95], v[132:135], v[182:185], v[92:95]
	v_mfma_f32_16x16x32_bf16 v[88:91], v[140:143], v[182:185], v[88:91]
	v_mfma_f32_16x16x32_bf16 v[76:79], v[132:135], v[190:193], v[76:79]
	v_mfma_f32_16x16x32_bf16 v[72:75], v[140:143], v[190:193], v[72:75]
	v_mfma_f32_16x16x32_bf16 v[116:119], v[194:197], v[144:147], 0
	v_mfma_f32_16x16x32_bf16 v[112:115], v[202:205], v[144:147], 0
	v_mfma_f32_16x16x32_bf16 v[100:103], v[194:197], v[166:169], 0
	v_mfma_f32_16x16x32_bf16 v[96:99], v[202:205], v[166:169], 0
	v_mfma_f32_16x16x32_bf16 v[84:87], v[194:197], v[178:181], 0
	v_mfma_f32_16x16x32_bf16 v[80:83], v[202:205], v[178:181], 0
	v_mfma_f32_16x16x32_bf16 v[68:71], v[194:197], v[186:189], 0
	v_mfma_f32_16x16x32_bf16 v[64:67], v[202:205], v[186:189], 0
	v_mfma_f32_16x16x32_bf16 v[116:119], v[198:201], v[148:151], v[116:119]
	v_mfma_f32_16x16x32_bf16 v[112:115], v[206:209], v[148:151], v[112:115]
	v_mfma_f32_16x16x32_bf16 v[100:103], v[198:201], v[174:177], v[100:103]
	v_mfma_f32_16x16x32_bf16 v[96:99], v[206:209], v[174:177], v[96:99]
	v_mfma_f32_16x16x32_bf16 v[84:87], v[198:201], v[182:185], v[84:87]
	v_mfma_f32_16x16x32_bf16 v[80:83], v[206:209], v[182:185], v[80:83]
	v_mfma_f32_16x16x32_bf16 v[68:71], v[198:201], v[190:193], v[68:71]
	s_setprio 0
	v_mfma_f32_16x16x32_bf16 v[64:67], v[206:209], v[190:193], v[64:67]
	s_barrier
	s_mov_b32 m0, s39
	v_lshl_add_u64 v[210:211], s[14:15], 0, v[156:157]
	global_load_lds_dwordx4 v[210:211], off
	s_add_i32 m0, s39, 0x2000
	v_lshl_add_u64 v[210:211], s[14:15], 0, v[158:159]
	global_load_lds_dwordx4 v[210:211], off
	s_mov_b32 m0, s25
	v_lshl_add_u64 v[210:211], s[18:19], 0, v[156:157]
	global_load_lds_dwordx4 v[210:211], off
	s_mov_b32 m0, s26
	v_lshl_add_u64 v[210:211], s[18:19], 0, v[158:159]
	global_load_lds_dwordx4 v[210:211], off
	s_add_u32 s40, s14, 0x80000
	s_addc_u32 s41, s15, 0
	s_add_i32 s39, s42, s23
	s_mov_b32 m0, s39
	v_lshl_add_u64 v[210:211], s[40:41], 0, v[156:157]
	global_load_lds_dwordx4 v[210:211], off
	s_add_i32 m0, s39, 0x2000
	v_lshl_add_u64 v[210:211], s[40:41], 0, v[158:159]
	global_load_lds_dwordx4 v[210:211], off
	ds_read_b128 v[144:147], v172 offset:16384
	ds_read_b128 v[166:169], v172 offset:18432
	ds_read_b128 v[178:181], v172 offset:20480
	ds_read_b128 v[186:189], v172 offset:22528
	ds_read_b128 v[148:151], v172 offset:17408
	ds_read_b128 v[174:177], v172 offset:19456
	ds_read_b128 v[182:185], v172 offset:21504
	ds_read_b128 v[190:193], v172 offset:23552
	s_waitcnt vmcnt(6)
	s_waitcnt lgkmcnt(0)
	s_barrier
; #define PG8_STAGE(bufoff, gbase, voff) do { _Pragma("unroll") for (int _i = 0; _i < 2; ++_i) \
;         __builtin_amdgcn_global_load_lds((const unsigned*)((const char*)(gbase) + (voff)[_i]), (LAS unsigned*)(lds + (bufoff) + ldsw + _i * 8192), 16, 0, 0); } while (0)
; #define PG8_LDA(dst, b, h) do { _Pragma("unroll") for (int m = 0; m < 4; ++m) _Pragma("unroll") for (int k = 0; k < 2; ++k) dst[m][k] = *(const LAS bf16x8*)(lds + PG8_SA(b, h) + aoff + m * 2048 + k * 1024); } while (0)
; #define PG8_LDB(dst, b, h) do { _Pragma("unroll") for (int n = 0; n < 2; ++n) _Pragma("unroll") for (int k = 0; k < 2; ++k) dst[n][k] = *(const LAS bf16x8*)(lds + PG8_SB(b, h) + boff + n * 2048 + k * 1024); } while (0)
; #define PG8_MMA(ai, bj, At, Bt) do { __builtin_amdgcn_s_setprio(1); _Pragma("unroll") for (int m = 0; m < 4; ++m) _Pragma("unroll") for (int n = 0; n < 2; ++n) _Pragma("unroll") for (int k = 0; k < 2; ++k) \
;         acc[ai][bj][m][n] = __builtin_amdgcn_mfma_f32_16x16x32_bf16(Bt[n][k], At[m][k], acc[ai][bj][m][n], 0, 0, 0); __builtin_amdgcn_s_setprio(0); } while (0)
; #define PG8_WAIT_V(n) asm volatile("s_waitcnt vmcnt(" #n ")" ::: "memory")
; #define PG8_WAIT_L(n) asm volatile("s_waitcnt lgkmcnt(" #n ")" ::: "memory")
; #define PG8_BAR __builtin_amdgcn_s_barrier()
; #define PG8_SCHED __builtin_amdgcn_sched_barrier(0)
; template <class Epi>
; __device__ __forceinline__ void gemm_phase(LAS unsigned char* lds, const Gemm g, const StaticOrder& S, const Epi& E) {
;     ...
;             PG8_BAR; PG8_WAIT_L(0); PG8_MMA(1, 0, At, B0); PG8_BAR; PG8_SCHED;
;             PG8_STAGE(PG8_SB(0, 1), b2 + hstepB, voffB);
;             PG8_WAIT_V(6); PG8_BAR; PG8_MMA(1, 1, At, B1); PG8_BAR;
;             PG8_LDB(B0, 1, 0); PG8_SCHED; PG8_LDA(At, 1, 0); PG8_STAGE(PG8_SA(0, 1), a2 + hstepA, voffA);
;             PG8_WAIT_L(8); PG8_BAR; PG8_WAIT_L(0); PG8_MMA(0, 0, At, B0); PG8_BAR; PG8_SCHED;
;             PG8_LDB(B1, 1, 1); PG8_STAGE(PG8_SB(1, 0), b3, voffB);
;             PG8_BAR; PG8_WAIT_L(0); PG8_MMA(0, 1, At, B1); PG8_BAR;
	v_mfma_f32_16x16x32_bf16 v[60:63], v[128:131], v[144:147], 0
	s_setprio 1
	v_mfma_f32_16x16x32_bf16 v[56:59], v[136:139], v[144:147], 0
	v_mfma_f32_16x16x32_bf16 v[44:47], v[128:131], v[166:169], 0
	v_mfma_f32_16x16x32_bf16 v[40:43], v[136:139], v[166:169], 0
	v_mfma_f32_16x16x32_bf16 v[28:31], v[128:131], v[178:181], 0
	v_mfma_f32_16x16x32_bf16 v[24:27], v[136:139], v[178:181], 0
	v_mfma_f32_16x16x32_bf16 v[12:15], v[128:131], v[186:189], 0
	v_mfma_f32_16x16x32_bf16 v[8:11], v[136:139], v[186:189], 0
	v_mfma_f32_16x16x32_bf16 v[60:63], v[132:135], v[148:151], v[60:63]
	v_mfma_f32_16x16x32_bf16 v[56:59], v[140:143], v[148:151], v[56:59]
	v_mfma_f32_16x16x32_bf16 v[44:47], v[132:135], v[174:177], v[44:47]
	v_mfma_f32_16x16x32_bf16 v[40:43], v[140:143], v[174:177], v[40:43]
	v_mfma_f32_16x16x32_bf16 v[28:31], v[132:135], v[182:185], v[28:31]
	v_mfma_f32_16x16x32_bf16 v[24:27], v[140:143], v[182:185], v[24:27]
	v_mfma_f32_16x16x32_bf16 v[12:15], v[132:135], v[190:193], v[12:15]
	v_mfma_f32_16x16x32_bf16 v[8:11], v[140:143], v[190:193], v[8:11]
	v_mfma_f32_16x16x32_bf16 v[52:55], v[194:197], v[144:147], 0
	v_mfma_f32_16x16x32_bf16 v[48:51], v[202:205], v[144:147], 0
	s_add_i32 s39, 0, 0x18000
	v_add_u32_e32 v140, s39, v170
	v_mfma_f32_16x16x32_bf16 v[36:39], v[194:197], v[166:169], 0
	v_mfma_f32_16x16x32_bf16 v[32:35], v[202:205], v[166:169], 0
	v_mfma_f32_16x16x32_bf16 v[20:23], v[194:197], v[178:181], 0
	v_mfma_f32_16x16x32_bf16 v[16:19], v[202:205], v[178:181], 0
	v_mfma_f32_16x16x32_bf16 v[4:7], v[194:197], v[186:189], 0
	v_mfma_f32_16x16x32_bf16 v[0:3], v[202:205], v[186:189], 0
	v_mfma_f32_16x16x32_bf16 v[52:55], v[198:201], v[148:151], v[52:55]
	v_mfma_f32_16x16x32_bf16 v[48:51], v[206:209], v[148:151], v[48:51]
	v_mfma_f32_16x16x32_bf16 v[36:39], v[198:201], v[174:177], v[36:39]
	v_mfma_f32_16x16x32_bf16 v[32:35], v[206:209], v[174:177], v[32:35]
	v_mfma_f32_16x16x32_bf16 v[20:23], v[198:201], v[182:185], v[20:23]
	v_mfma_f32_16x16x32_bf16 v[16:19], v[206:209], v[182:185], v[16:19]
	v_mfma_f32_16x16x32_bf16 v[4:7], v[198:201], v[190:193], v[4:7]
	s_setprio 0
	v_mfma_f32_16x16x32_bf16 v[0:3], v[206:209], v[190:193], v[0:3]
	s_barrier
	s_add_u32 s18, s18, 0x80000
	s_addc_u32 s19, s19, 0
	s_mov_b32 m0, s27
	v_lshl_add_u64 v[194:195], s[18:19], 0, v[156:157]
	global_load_lds_dwordx4 v[194:195], off
	s_mov_b32 m0, s28
	v_lshl_add_u64 v[194:195], s[18:19], 0, v[158:159]
	global_load_lds_dwordx4 v[194:195], off
	ds_read_b128 v[128:131], v140
	ds_read_b128 v[136:139], v140 offset:2048
	ds_read_b128 v[132:135], v140 offset:1024
	ds_read_b128 v[140:143], v140 offset:3072
	ds_read_b128 v[144:147], v172 offset:32768
	ds_read_b128 v[166:169], v172 offset:34816
	ds_read_b128 v[178:181], v172 offset:36864
	ds_read_b128 v[186:189], v172 offset:38912
	ds_read_b128 v[148:151], v172 offset:33792
	ds_read_b128 v[174:177], v172 offset:35840
	ds_read_b128 v[182:185], v172 offset:37888
	ds_read_b128 v[190:193], v172 offset:39936
	s_mov_b32 s40, 0x1c000
	s_add_u32 s18, s14, 0x4000
	s_addc_u32 s19, s15, 0
	s_add_i32 s39, s39, s23
	v_add_u32_e32 v152, s40, v170
	ds_read_b128 v[194:197], v152
	ds_read_b128 v[202:205], v152 offset:2048
	ds_read_b128 v[198:201], v152 offset:1024
	ds_read_b128 v[206:209], v152 offset:3072
	s_waitcnt lgkmcnt(0)
	s_barrier
	v_mfma_f32_16x16x32_bf16 v[124:127], v[128:131], v[144:147], v[124:127]
	s_setprio 1
	v_mfma_f32_16x16x32_bf16 v[120:123], v[136:139], v[144:147], v[120:123]
	v_mfma_f32_16x16x32_bf16 v[108:111], v[128:131], v[166:169], v[108:111]
	v_mfma_f32_16x16x32_bf16 v[104:107], v[136:139], v[166:169], v[104:107]
	v_mfma_f32_16x16x32_bf16 v[92:95], v[128:131], v[178:181], v[92:95]
	v_mfma_f32_16x16x32_bf16 v[88:91], v[136:139], v[178:181], v[88:91]
	v_mfma_f32_16x16x32_bf16 v[76:79], v[128:131], v[186:189], v[76:79]
	v_mfma_f32_16x16x32_bf16 v[72:75], v[136:139], v[186:189], v[72:75]
	v_mfma_f32_16x16x32_bf16 v[124:127], v[132:135], v[148:151], v[124:127]
	v_mfma_f32_16x16x32_bf16 v[120:123], v[140:143], v[148:151], v[120:123]
	v_mfma_f32_16x16x32_bf16 v[108:111], v[132:135], v[174:177], v[108:111]
	v_mfma_f32_16x16x32_bf16 v[104:107], v[140:143], v[174:177], v[104:107]
	v_mfma_f32_16x16x32_bf16 v[92:95], v[132:135], v[182:185], v[92:95]
	v_mfma_f32_16x16x32_bf16 v[88:91], v[140:143], v[182:185], v[88:91]
	v_mfma_f32_16x16x32_bf16 v[76:79], v[132:135], v[190:193], v[76:79]
	v_mfma_f32_16x16x32_bf16 v[72:75], v[140:143], v[190:193], v[72:75]
	v_mfma_f32_16x16x32_bf16 v[116:119], v[194:197], v[144:147], v[116:119]
	v_mfma_f32_16x16x32_bf16 v[112:115], v[202:205], v[144:147], v[112:115]
	v_mfma_f32_16x16x32_bf16 v[100:103], v[194:197], v[166:169], v[100:103]
	v_mfma_f32_16x16x32_bf16 v[96:99], v[202:205], v[166:169], v[96:99]
	v_mfma_f32_16x16x32_bf16 v[84:87], v[194:197], v[178:181], v[84:87]
	v_mfma_f32_16x16x32_bf16 v[80:83], v[202:205], v[178:181], v[80:83]
	v_mfma_f32_16x16x32_bf16 v[68:71], v[194:197], v[186:189], v[68:71]
	v_mfma_f32_16x16x32_bf16 v[64:67], v[202:205], v[186:189], v[64:67]
	v_mfma_f32_16x16x32_bf16 v[116:119], v[198:201], v[148:151], v[116:119]
	v_mfma_f32_16x16x32_bf16 v[112:115], v[206:209], v[148:151], v[112:115]
	v_mfma_f32_16x16x32_bf16 v[100:103], v[198:201], v[174:177], v[100:103]
	v_mfma_f32_16x16x32_bf16 v[96:99], v[206:209], v[174:177], v[96:99]
	v_mfma_f32_16x16x32_bf16 v[84:87], v[198:201], v[182:185], v[84:87]
	v_mfma_f32_16x16x32_bf16 v[80:83], v[206:209], v[182:185], v[80:83]
	v_mfma_f32_16x16x32_bf16 v[68:71], v[198:201], v[190:193], v[68:71]
	s_setprio 0
	v_mfma_f32_16x16x32_bf16 v[64:67], v[206:209], v[190:193], v[64:67]
	s_barrier
; #define PG8_STAGE(bufoff, gbase, voff) do { _Pragma("unroll") for (int _i = 0; _i < 2; ++_i) \
;         __builtin_amdgcn_global_load_lds((const unsigned*)((const char*)(gbase) + (voff)[_i]), (LAS unsigned*)(lds + (bufoff) + ldsw + _i * 8192), 16, 0, 0); } while (0)
; #define PG8_LDA(dst, b, h) do { _Pragma("unroll") for (int m = 0; m < 4; ++m) _Pragma("unroll") for (int k = 0; k < 2; ++k) dst[m][k] = *(const LAS bf16x8*)(lds + PG8_SA(b, h) + aoff + m * 2048 + k * 1024); } while (0)
; #define PG8_LDB(dst, b, h) do { _Pragma("unroll") for (int n = 0; n < 2; ++n) _Pragma("unroll") for (int k = 0; k < 2; ++k) dst[n][k] = *(const LAS bf16x8*)(lds + PG8_SB(b, h) + boff + n * 2048 + k * 1024); } while (0)
; #define PG8_MMA(ai, bj, At, Bt) do { __builtin_amdgcn_s_setprio(1); _Pragma("unroll") for (int m = 0; m < 4; ++m) _Pragma("unroll") for (int n = 0; n < 2; ++n) _Pragma("unroll") for (int k = 0; k < 2; ++k) \
;         acc[ai][bj][m][n] = __builtin_amdgcn_mfma_f32_16x16x32_bf16(Bt[n][k], At[m][k], acc[ai][bj][m][n], 0, 0, 0); __builtin_amdgcn_s_setprio(0); } while (0)
; #define PG8_WAIT_V(n) asm volatile("s_waitcnt vmcnt(" #n ")" ::: "memory")
; #define PG8_WAIT_L(n) asm volatile("s_waitcnt lgkmcnt(" #n ")" ::: "memory")
; #define PG8_BAR __builtin_amdgcn_s_barrier()
; #define PG8_SCHED __builtin_amdgcn_sched_barrier(0)
; template <class Epi>
; __device__ __forceinline__ void gemm_phase(LAS unsigned char* lds, const Gemm g, const StaticOrder& S, const Epi& E) {
;     ...
;             const bool last = (t == nt - 2);
;             const char* a1 = cA + (size_t)(t + 1) * kstep;
;             const char* a2 = last ? nA : cA + (size_t)(t + 2) * kstep; const char* b2 = last ? nB : cB + (size_t)(t + 2) * kstep;
;             const char* a3 = a2 + kstep; const char* b3 = b2 + kstep;
;             PG8_LDB(B0, 0, 0); PG8_SCHED; PG8_LDA(At, 0, 0); PG8_STAGE(PG8_SA(1, 1), a1 + hstepA, voffA);
;             PG8_WAIT_L(8); PG8_BAR; PG8_WAIT_L(0); PG8_MMA(0, 0, At, B0); PG8_BAR; PG8_SCHED;
;             PG8_LDB(B1, 0, 1); PG8_STAGE(PG8_SB(0, 0), b2, voffB);
;     ...
;             PG8_LDA(At, 1, 1); PG8_STAGE(PG8_SA(1, 0), a3, voffA);
;             PG8_BAR; PG8_WAIT_L(0); PG8_MMA(1, 0, At, B0); PG8_BAR; PG8_SCHED;
;             PG8_STAGE(PG8_SB(1, 1), b3 + hstepB, voffB);
;             PG8_WAIT_V(6); PG8_BAR; PG8_MMA(1, 1, At, B1); PG8_BAR;
	s_mov_b32 m0, s39
	v_lshl_add_u64 v[210:211], s[18:19], 0, v[156:157]
	global_load_lds_dwordx4 v[210:211], off
	s_add_i32 m0, s39, 0x2000
	v_lshl_add_u64 v[210:211], s[18:19], 0, v[158:159]
	global_load_lds_dwordx4 v[210:211], off
	s_mov_b32 m0, s29
	v_lshl_add_u64 v[210:211], s[16:17], 0, v[156:157]
	global_load_lds_dwordx4 v[210:211], off
	s_mov_b32 m0, s30
	v_lshl_add_u64 v[210:211], s[16:17], 0, v[158:159]
	global_load_lds_dwordx4 v[210:211], off
	s_add_u32 s14, s14, 0x84000
	s_addc_u32 s15, s15, 0
	s_add_i32 s16, s40, s23
	s_mov_b32 m0, s16
	v_lshl_add_u64 v[210:211], s[14:15], 0, v[156:157]
	global_load_lds_dwordx4 v[210:211], off
	s_add_i32 m0, s16, 0x2000
	v_lshl_add_u64 v[210:211], s[14:15], 0, v[158:159]
	global_load_lds_dwordx4 v[210:211], off
	ds_read_b128 v[144:147], v172 offset:49152
	ds_read_b128 v[166:169], v172 offset:51200
	ds_read_b128 v[178:181], v172 offset:53248
	ds_read_b128 v[186:189], v172 offset:55296
	ds_read_b128 v[148:151], v172 offset:50176
	ds_read_b128 v[174:177], v172 offset:52224
	ds_read_b128 v[182:185], v172 offset:54272
	ds_read_b128 v[190:193], v172 offset:56320
	s_waitcnt vmcnt(6)
	s_waitcnt lgkmcnt(0)
	s_barrier
	v_mfma_f32_16x16x32_bf16 v[60:63], v[128:131], v[144:147], v[60:63]
	s_setprio 1
	v_mfma_f32_16x16x32_bf16 v[56:59], v[136:139], v[144:147], v[56:59]
	v_mfma_f32_16x16x32_bf16 v[44:47], v[128:131], v[166:169], v[44:47]
	v_mfma_f32_16x16x32_bf16 v[40:43], v[136:139], v[166:169], v[40:43]
	v_mfma_f32_16x16x32_bf16 v[28:31], v[128:131], v[178:181], v[28:31]
	v_mfma_f32_16x16x32_bf16 v[24:27], v[136:139], v[178:181], v[24:27]
	v_mfma_f32_16x16x32_bf16 v[12:15], v[128:131], v[186:189], v[12:15]
	v_mfma_f32_16x16x32_bf16 v[8:11], v[136:139], v[186:189], v[8:11]
	v_mfma_f32_16x16x32_bf16 v[60:63], v[132:135], v[148:151], v[60:63]
	v_mfma_f32_16x16x32_bf16 v[56:59], v[140:143], v[148:151], v[56:59]
	v_mfma_f32_16x16x32_bf16 v[44:47], v[132:135], v[174:177], v[44:47]
	v_mfma_f32_16x16x32_bf16 v[40:43], v[140:143], v[174:177], v[40:43]
	v_mfma_f32_16x16x32_bf16 v[28:31], v[132:135], v[182:185], v[28:31]
	v_mfma_f32_16x16x32_bf16 v[24:27], v[140:143], v[182:185], v[24:27]
	v_mfma_f32_16x16x32_bf16 v[12:15], v[132:135], v[190:193], v[12:15]
	v_mfma_f32_16x16x32_bf16 v[8:11], v[140:143], v[190:193], v[8:11]
	v_mfma_f32_16x16x32_bf16 v[52:55], v[194:197], v[144:147], v[52:55]
	v_mfma_f32_16x16x32_bf16 v[48:51], v[202:205], v[144:147], v[48:51]
	s_add_i32 s38, s38, 2
	s_add_u32 s12, s12, 0x8000
	s_addc_u32 s13, s13, 0
	s_add_u32 s36, s36, 0x8000
	s_addc_u32 s37, s37, 0
	v_mfma_f32_16x16x32_bf16 v[36:39], v[194:197], v[166:169], v[36:39]
	v_mfma_f32_16x16x32_bf16 v[32:35], v[202:205], v[166:169], v[32:35]
	v_mfma_f32_16x16x32_bf16 v[20:23], v[194:197], v[178:181], v[20:23]
	v_mfma_f32_16x16x32_bf16 v[16:19], v[202:205], v[178:181], v[16:19]
	v_mfma_f32_16x16x32_bf16 v[4:7], v[194:197], v[186:189], v[4:7]
	v_mfma_f32_16x16x32_bf16 v[0:3], v[202:205], v[186:189], v[0:3]
	v_mfma_f32_16x16x32_bf16 v[52:55], v[198:201], v[148:151], v[52:55]
	v_mfma_f32_16x16x32_bf16 v[48:51], v[206:209], v[148:151], v[48:51]
	v_mfma_f32_16x16x32_bf16 v[36:39], v[198:201], v[174:177], v[36:39]
	v_mfma_f32_16x16x32_bf16 v[32:35], v[206:209], v[174:177], v[32:35]
	v_mfma_f32_16x16x32_bf16 v[20:23], v[198:201], v[182:185], v[20:23]
	v_mfma_f32_16x16x32_bf16 v[16:19], v[206:209], v[182:185], v[16:19]
	v_mfma_f32_16x16x32_bf16 v[4:7], v[198:201], v[190:193], v[4:7]
	s_cmp_gt_u32 s38, 29
	s_setprio 0
	v_mfma_f32_16x16x32_bf16 v[0:3], v[206:209], v[190:193], v[0:3]
	s_barrier
	s_cbranch_scc0 .LBB0_247
	s_branch .Lpeel_done_247
.LBB0_247:
	s_add_u32 s14, s12, 0xfff84000
	s_addc_u32 s15, s13, -1
	s_cmp_eq_u32 s38, 28
	s_cselect_b32 s18, s11, s14
	s_cselect_b32 s19, s5, s15
	s_cselect_b32 s14, s35, s36
	s_cselect_b32 s15, s3, s37
	s_add_u32 s16, s18, 0x4000
	s_addc_u32 s17, s19, 0
	s_add_i32 m0, s25, 0xc000
	v_lshl_add_u64 v[194:195], s[12:13], 0, v[156:157]
	global_load_lds_dwordx4 v[194:195], off
	s_add_i32 m0, s25, 0xe000
	v_lshl_add_u64 v[194:195], s[12:13], 0, v[158:159]
	global_load_lds_dwordx4 v[194:195], off
	s_mov_b32 s39, 0x10000
	v_add_u32_e32 v140, s39, v170
	ds_read_b128 v[128:131], v140
	ds_read_b128 v[136:139], v140 offset:2048
	ds_read_b128 v[132:135], v140 offset:1024
	ds_read_b128 v[140:143], v140 offset:3072
	ds_read_b128 v[144:147], v172
	ds_read_b128 v[166:169], v172 offset:2048
	ds_read_b128 v[178:181], v172 offset:4096
	ds_read_b128 v[186:189], v172 offset:6144
	ds_read_b128 v[148:151], v172 offset:1024
	ds_read_b128 v[174:177], v172 offset:3072
	ds_read_b128 v[182:185], v172 offset:5120
	ds_read_b128 v[190:193], v172 offset:7168
	s_mov_b32 s42, 0x14000
	s_add_i32 s39, s39, s23
	v_add_u32_e32 v152, s42, v170
	ds_read_b128 v[194:197], v152
	ds_read_b128 v[202:205], v152 offset:2048
	ds_read_b128 v[198:201], v152 offset:1024
	ds_read_b128 v[206:209], v152 offset:3072
	s_waitcnt lgkmcnt(0)
	s_barrier
; #define PG8_STAGE(bufoff, gbase, voff) do { _Pragma("unroll") for (int _i = 0; _i < 2; ++_i) \
;         __builtin_amdgcn_global_load_lds((const unsigned*)((const char*)(gbase) + (voff)[_i]), (LAS unsigned*)(lds + (bufoff) + ldsw + _i * 8192), 16, 0, 0); } while (0)
; #define PG8_LDA(dst, b, h) do { _Pragma("unroll") for (int m = 0; m < 4; ++m) _Pragma("unroll") for (int k = 0; k < 2; ++k) dst[m][k] = *(const LAS bf16x8*)(lds + PG8_SA(b, h) + aoff + m * 2048 + k * 1024); } while (0)
; #define PG8_LDB(dst, b, h) do { _Pragma("unroll") for (int n = 0; n < 2; ++n) _Pragma("unroll") for (int k = 0; k < 2; ++k) dst[n][k] = *(const LAS bf16x8*)(lds + PG8_SB(b, h) + boff + n * 2048 + k * 1024); } while (0)
; #define PG8_MMA(ai, bj, At, Bt) do { __builtin_amdgcn_s_setprio(1); _Pragma("unroll") for (int m = 0; m < 4; ++m) _Pragma("unroll") for (int n = 0; n < 2; ++n) _Pragma("unroll") for (int k = 0; k < 2; ++k) \
;         acc[ai][bj][m][n] = __builtin_amdgcn_mfma_f32_16x16x32_bf16(Bt[n][k], At[m][k], acc[ai][bj][m][n], 0, 0, 0); __builtin_amdgcn_s_setprio(0); } while (0)
; #define PG8_WAIT_V(n) asm volatile("s_waitcnt vmcnt(" #n ")" ::: "memory")
; #define PG8_WAIT_L(n) asm volatile("s_waitcnt lgkmcnt(" #n ")" ::: "memory")
; #define PG8_BAR __builtin_amdgcn_s_barrier()
; #define PG8_SCHED __builtin_amdgcn_sched_barrier(0)
; template <class Epi>
; __device__ __forceinline__ void gemm_phase(LAS unsigned char* lds, const Gemm g, const StaticOrder& S, const Epi& E) {
;     ...
;             PG8_WAIT_L(8); PG8_BAR; PG8_WAIT_L(0); PG8_MMA(0, 0, At, B0); PG8_BAR; PG8_SCHED;
;             PG8_LDB(B1, 0, 1); PG8_STAGE(PG8_SB(0, 0), b2, voffB);
;             PG8_BAR; PG8_WAIT_L(0); PG8_MMA(0, 1, At, B1); PG8_BAR;
;             PG8_LDA(At, 0, 1); PG8_STAGE(PG8_SA(0, 0), a2, voffA);
;             PG8_BAR; PG8_WAIT_L(0); PG8_MMA(1, 0, At, B0); PG8_BAR; PG8_SCHED;
;             PG8_STAGE(PG8_SB(0, 1), b2 + hstepB, voffB);
;             PG8_WAIT_V(6); PG8_BAR; PG8_MMA(1, 1, At, B1); PG8_BAR;
	v_mfma_f32_16x16x32_bf16 v[124:127], v[128:131], v[144:147], v[124:127]
	s_setprio 1
	v_mfma_f32_16x16x32_bf16 v[120:123], v[136:139], v[144:147], v[120:123]
	v_mfma_f32_16x16x32_bf16 v[108:111], v[128:131], v[166:169], v[108:111]
	v_mfma_f32_16x16x32_bf16 v[104:107], v[136:139], v[166:169], v[104:107]
	v_mfma_f32_16x16x32_bf16 v[92:95], v[128:131], v[178:181], v[92:95]
	v_mfma_f32_16x16x32_bf16 v[88:91], v[136:139], v[178:181], v[88:91]
	v_mfma_f32_16x16x32_bf16 v[76:79], v[128:131], v[186:189], v[76:79]
	v_mfma_f32_16x16x32_bf16 v[72:75], v[136:139], v[186:189], v[72:75]
	v_mfma_f32_16x16x32_bf16 v[124:127], v[132:135], v[148:151], v[124:127]
	v_mfma_f32_16x16x32_bf16 v[120:123], v[140:143], v[148:151], v[120:123]
	v_mfma_f32_16x16x32_bf16 v[108:111], v[132:135], v[174:177], v[108:111]
	v_mfma_f32_16x16x32_bf16 v[104:107], v[140:143], v[174:177], v[104:107]
	v_mfma_f32_16x16x32_bf16 v[92:95], v[132:135], v[182:185], v[92:95]
	v_mfma_f32_16x16x32_bf16 v[88:91], v[140:143], v[182:185], v[88:91]
	v_mfma_f32_16x16x32_bf16 v[76:79], v[132:135], v[190:193], v[76:79]
	v_mfma_f32_16x16x32_bf16 v[72:75], v[140:143], v[190:193], v[72:75]
	v_mfma_f32_16x16x32_bf16 v[116:119], v[194:197], v[144:147], v[116:119]
	v_mfma_f32_16x16x32_bf16 v[112:115], v[202:205], v[144:147], v[112:115]
	v_mfma_f32_16x16x32_bf16 v[100:103], v[194:197], v[166:169], v[100:103]
	v_mfma_f32_16x16x32_bf16 v[96:99], v[202:205], v[166:169], v[96:99]
	v_mfma_f32_16x16x32_bf16 v[84:87], v[194:197], v[178:181], v[84:87]
	v_mfma_f32_16x16x32_bf16 v[80:83], v[202:205], v[178:181], v[80:83]
	v_mfma_f32_16x16x32_bf16 v[68:71], v[194:197], v[186:189], v[68:71]
	v_mfma_f32_16x16x32_bf16 v[64:67], v[202:205], v[186:189], v[64:67]
	v_mfma_f32_16x16x32_bf16 v[116:119], v[198:201], v[148:151], v[116:119]
	v_mfma_f32_16x16x32_bf16 v[112:115], v[206:209], v[148:151], v[112:115]
	v_mfma_f32_16x16x32_bf16 v[100:103], v[198:201], v[174:177], v[100:103]
	v_mfma_f32_16x16x32_bf16 v[96:99], v[206:209], v[174:177], v[96:99]
	v_mfma_f32_16x16x32_bf16 v[84:87], v[198:201], v[182:185], v[84:87]
	v_mfma_f32_16x16x32_bf16 v[80:83], v[206:209], v[182:185], v[80:83]
	v_mfma_f32_16x16x32_bf16 v[68:71], v[198:201], v[190:193], v[68:71]
	s_setprio 0
	v_mfma_f32_16x16x32_bf16 v[64:67], v[206:209], v[190:193], v[64:67]
	s_barrier
	s_mov_b32 m0, s39
	v_lshl_add_u64 v[210:211], s[14:15], 0, v[156:157]
	global_load_lds_dwordx4 v[210:211], off
	s_add_i32 m0, s39, 0x2000
	v_lshl_add_u64 v[210:211], s[14:15], 0, v[158:159]
	global_load_lds_dwordx4 v[210:211], off
	s_mov_b32 m0, s25
	v_lshl_add_u64 v[210:211], s[18:19], 0, v[156:157]
	global_load_lds_dwordx4 v[210:211], off
	s_mov_b32 m0, s26
	v_lshl_add_u64 v[210:211], s[18:19], 0, v[158:159]
	global_load_lds_dwordx4 v[210:211], off
	s_add_u32 s40, s14, 0x80000
	s_addc_u32 s41, s15, 0
	s_add_i32 s39, s42, s23
	s_mov_b32 m0, s39
	v_lshl_add_u64 v[210:211], s[40:41], 0, v[156:157]
	global_load_lds_dwordx4 v[210:211], off
	s_add_i32 m0, s39, 0x2000
	v_lshl_add_u64 v[210:211], s[40:41], 0, v[158:159]
	global_load_lds_dwordx4 v[210:211], off
	ds_read_b128 v[144:147], v172 offset:16384
	ds_read_b128 v[166:169], v172 offset:18432
	ds_read_b128 v[178:181], v172 offset:20480
	ds_read_b128 v[186:189], v172 offset:22528
	ds_read_b128 v[148:151], v172 offset:17408
	ds_read_b128 v[174:177], v172 offset:19456
	ds_read_b128 v[182:185], v172 offset:21504
	ds_read_b128 v[190:193], v172 offset:23552
	s_waitcnt vmcnt(6)
	s_waitcnt lgkmcnt(0)
	s_barrier
	v_mfma_f32_16x16x32_bf16 v[60:63], v[128:131], v[144:147], v[60:63]
	s_setprio 1
	v_mfma_f32_16x16x32_bf16 v[56:59], v[136:139], v[144:147], v[56:59]
	v_mfma_f32_16x16x32_bf16 v[44:47], v[128:131], v[166:169], v[44:47]
	v_mfma_f32_16x16x32_bf16 v[40:43], v[136:139], v[166:169], v[40:43]
	v_mfma_f32_16x16x32_bf16 v[28:31], v[128:131], v[178:181], v[28:31]
	v_mfma_f32_16x16x32_bf16 v[24:27], v[136:139], v[178:181], v[24:27]
	v_mfma_f32_16x16x32_bf16 v[12:15], v[128:131], v[186:189], v[12:15]
	v_mfma_f32_16x16x32_bf16 v[8:11], v[136:139], v[186:189], v[8:11]
	v_mfma_f32_16x16x32_bf16 v[60:63], v[132:135], v[148:151], v[60:63]
	v_mfma_f32_16x16x32_bf16 v[56:59], v[140:143], v[148:151], v[56:59]
	v_mfma_f32_16x16x32_bf16 v[44:47], v[132:135], v[174:177], v[44:47]
	v_mfma_f32_16x16x32_bf16 v[40:43], v[140:143], v[174:177], v[40:43]
	v_mfma_f32_16x16x32_bf16 v[28:31], v[132:135], v[182:185], v[28:31]
	v_mfma_f32_16x16x32_bf16 v[24:27], v[140:143], v[182:185], v[24:27]
	v_mfma_f32_16x16x32_bf16 v[12:15], v[132:135], v[190:193], v[12:15]
	v_mfma_f32_16x16x32_bf16 v[8:11], v[140:143], v[190:193], v[8:11]
	v_mfma_f32_16x16x32_bf16 v[52:55], v[194:197], v[144:147], v[52:55]
	v_mfma_f32_16x16x32_bf16 v[48:51], v[202:205], v[144:147], v[48:51]
	s_add_i32 s39, 0, 0x18000
	v_add_u32_e32 v140, s39, v170
	v_mfma_f32_16x16x32_bf16 v[36:39], v[194:197], v[166:169], v[36:39]
	v_mfma_f32_16x16x32_bf16 v[32:35], v[202:205], v[166:169], v[32:35]
	v_mfma_f32_16x16x32_bf16 v[20:23], v[194:197], v[178:181], v[20:23]
	v_mfma_f32_16x16x32_bf16 v[16:19], v[202:205], v[178:181], v[16:19]
	v_mfma_f32_16x16x32_bf16 v[4:7], v[194:197], v[186:189], v[4:7]
	v_mfma_f32_16x16x32_bf16 v[0:3], v[202:205], v[186:189], v[0:3]
	v_mfma_f32_16x16x32_bf16 v[52:55], v[198:201], v[148:151], v[52:55]
	v_mfma_f32_16x16x32_bf16 v[48:51], v[206:209], v[148:151], v[48:51]
	v_mfma_f32_16x16x32_bf16 v[36:39], v[198:201], v[174:177], v[36:39]
	v_mfma_f32_16x16x32_bf16 v[32:35], v[206:209], v[174:177], v[32:35]
	v_mfma_f32_16x16x32_bf16 v[20:23], v[198:201], v[182:185], v[20:23]
	v_mfma_f32_16x16x32_bf16 v[16:19], v[206:209], v[182:185], v[16:19]
	v_mfma_f32_16x16x32_bf16 v[4:7], v[198:201], v[190:193], v[4:7]
	s_setprio 0
	v_mfma_f32_16x16x32_bf16 v[0:3], v[206:209], v[190:193], v[0:3]
	s_barrier
; #define PG8_STAGE(bufoff, gbase, voff) do { _Pragma("unroll") for (int _i = 0; _i < 2; ++_i) \
;         __builtin_amdgcn_global_load_lds((const unsigned*)((const char*)(gbase) + (voff)[_i]), (LAS unsigned*)(lds + (bufoff) + ldsw + _i * 8192), 16, 0, 0); } while (0)
; #define PG8_LDA(dst, b, h) do { _Pragma("unroll") for (int m = 0; m < 4; ++m) _Pragma("unroll") for (int k = 0; k < 2; ++k) dst[m][k] = *(const LAS bf16x8*)(lds + PG8_SA(b, h) + aoff + m * 2048 + k * 1024); } while (0)
; #define PG8_LDB(dst, b, h) do { _Pragma("unroll") for (int n = 0; n < 2; ++n) _Pragma("unroll") for (int k = 0; k < 2; ++k) dst[n][k] = *(const LAS bf16x8*)(lds + PG8_SB(b, h) + boff + n * 2048 + k * 1024); } while (0)
; #define PG8_MMA(ai, bj, At, Bt) do { __builtin_amdgcn_s_setprio(1); _Pragma("unroll") for (int m = 0; m < 4; ++m) _Pragma("unroll") for (int n = 0; n < 2; ++n) _Pragma("unroll") for (int k = 0; k < 2; ++k) \
;         acc[ai][bj][m][n] = __builtin_amdgcn_mfma_f32_16x16x32_bf16(Bt[n][k], At[m][k], acc[ai][bj][m][n], 0, 0, 0); __builtin_amdgcn_s_setprio(0); } while (0)
; #define PG8_WAIT_V(n) asm volatile("s_waitcnt vmcnt(" #n ")" ::: "memory")
; #define PG8_WAIT_L(n) asm volatile("s_waitcnt lgkmcnt(" #n ")" ::: "memory")
; #define PG8_BAR __builtin_amdgcn_s_barrier()
; #define PG8_SCHED __builtin_amdgcn_sched_barrier(0)
; template <class Epi>
; __device__ __forceinline__ void gemm_phase(LAS unsigned char* lds, const Gemm g, const StaticOrder& S, const Epi& E) {
;     ...
;             PG8_LDB(B0, 1, 0); PG8_SCHED; PG8_LDA(At, 1, 0); PG8_STAGE(PG8_SA(0, 1), a2 + hstepA, voffA);
;             PG8_WAIT_L(8); PG8_BAR; PG8_WAIT_L(0); PG8_MMA(0, 0, At, B0); PG8_BAR; PG8_SCHED;
;             PG8_LDB(B1, 1, 1); PG8_STAGE(PG8_SB(1, 0), b3, voffB);
;             PG8_BAR; PG8_WAIT_L(0); PG8_MMA(0, 1, At, B1); PG8_BAR;
;             PG8_LDA(At, 1, 1); PG8_STAGE(PG8_SA(1, 0), a3, voffA);
;             PG8_BAR; PG8_WAIT_L(0); PG8_MMA(1, 0, At, B0); PG8_BAR; PG8_SCHED;
;             PG8_STAGE(PG8_SB(1, 1), b3 + hstepB, voffB);
;             PG8_WAIT_V(6); PG8_BAR; PG8_MMA(1, 1, At, B1); PG8_BAR;
	s_add_u32 s18, s18, 0x80000
	s_addc_u32 s19, s19, 0
	s_mov_b32 m0, s27
	v_lshl_add_u64 v[194:195], s[18:19], 0, v[156:157]
	global_load_lds_dwordx4 v[194:195], off
	s_mov_b32 m0, s28
	v_lshl_add_u64 v[194:195], s[18:19], 0, v[158:159]
	global_load_lds_dwordx4 v[194:195], off
	ds_read_b128 v[128:131], v140
	ds_read_b128 v[136:139], v140 offset:2048
	ds_read_b128 v[132:135], v140 offset:1024
	ds_read_b128 v[140:143], v140 offset:3072
	ds_read_b128 v[144:147], v172 offset:32768
	ds_read_b128 v[166:169], v172 offset:34816
	ds_read_b128 v[178:181], v172 offset:36864
	ds_read_b128 v[186:189], v172 offset:38912
	ds_read_b128 v[148:151], v172 offset:33792
	ds_read_b128 v[174:177], v172 offset:35840
	ds_read_b128 v[182:185], v172 offset:37888
	ds_read_b128 v[190:193], v172 offset:39936
	s_mov_b32 s40, 0x1c000
	s_add_u32 s18, s14, 0x4000
	s_addc_u32 s19, s15, 0
	s_add_i32 s39, s39, s23
	v_add_u32_e32 v152, s40, v170
	ds_read_b128 v[194:197], v152
	ds_read_b128 v[202:205], v152 offset:2048
	ds_read_b128 v[198:201], v152 offset:1024
	ds_read_b128 v[206:209], v152 offset:3072
	s_waitcnt lgkmcnt(0)
	s_barrier
	v_mfma_f32_16x16x32_bf16 v[124:127], v[128:131], v[144:147], v[124:127]
	s_setprio 1
	v_mfma_f32_16x16x32_bf16 v[120:123], v[136:139], v[144:147], v[120:123]
	v_mfma_f32_16x16x32_bf16 v[108:111], v[128:131], v[166:169], v[108:111]
	v_mfma_f32_16x16x32_bf16 v[104:107], v[136:139], v[166:169], v[104:107]
	v_mfma_f32_16x16x32_bf16 v[92:95], v[128:131], v[178:181], v[92:95]
	v_mfma_f32_16x16x32_bf16 v[88:91], v[136:139], v[178:181], v[88:91]
	v_mfma_f32_16x16x32_bf16 v[76:79], v[128:131], v[186:189], v[76:79]
	v_mfma_f32_16x16x32_bf16 v[72:75], v[136:139], v[186:189], v[72:75]
	v_mfma_f32_16x16x32_bf16 v[124:127], v[132:135], v[148:151], v[124:127]
	v_mfma_f32_16x16x32_bf16 v[120:123], v[140:143], v[148:151], v[120:123]
	v_mfma_f32_16x16x32_bf16 v[108:111], v[132:135], v[174:177], v[108:111]
	v_mfma_f32_16x16x32_bf16 v[104:107], v[140:143], v[174:177], v[104:107]
	v_mfma_f32_16x16x32_bf16 v[92:95], v[132:135], v[182:185], v[92:95]
	v_mfma_f32_16x16x32_bf16 v[88:91], v[140:143], v[182:185], v[88:91]
	v_mfma_f32_16x16x32_bf16 v[76:79], v[132:135], v[190:193], v[76:79]
	v_mfma_f32_16x16x32_bf16 v[72:75], v[140:143], v[190:193], v[72:75]
	v_mfma_f32_16x16x32_bf16 v[116:119], v[194:197], v[144:147], v[116:119]
	v_mfma_f32_16x16x32_bf16 v[112:115], v[202:205], v[144:147], v[112:115]
	v_mfma_f32_16x16x32_bf16 v[100:103], v[194:197], v[166:169], v[100:103]
	v_mfma_f32_16x16x32_bf16 v[96:99], v[202:205], v[166:169], v[96:99]
	v_mfma_f32_16x16x32_bf16 v[84:87], v[194:197], v[178:181], v[84:87]
	v_mfma_f32_16x16x32_bf16 v[80:83], v[202:205], v[178:181], v[80:83]
	v_mfma_f32_16x16x32_bf16 v[68:71], v[194:197], v[186:189], v[68:71]
	v_mfma_f32_16x16x32_bf16 v[64:67], v[202:205], v[186:189], v[64:67]
	v_mfma_f32_16x16x32_bf16 v[116:119], v[198:201], v[148:151], v[116:119]
	v_mfma_f32_16x16x32_bf16 v[112:115], v[206:209], v[148:151], v[112:115]
	v_mfma_f32_16x16x32_bf16 v[100:103], v[198:201], v[174:177], v[100:103]
	v_mfma_f32_16x16x32_bf16 v[96:99], v[206:209], v[174:177], v[96:99]
	v_mfma_f32_16x16x32_bf16 v[84:87], v[198:201], v[182:185], v[84:87]
	v_mfma_f32_16x16x32_bf16 v[80:83], v[206:209], v[182:185], v[80:83]
	v_mfma_f32_16x16x32_bf16 v[68:71], v[198:201], v[190:193], v[68:71]
	s_setprio 0
	v_mfma_f32_16x16x32_bf16 v[64:67], v[206:209], v[190:193], v[64:67]
	s_barrier
	s_mov_b32 m0, s39
	v_lshl_add_u64 v[210:211], s[18:19], 0, v[156:157]
	global_load_lds_dwordx4 v[210:211], off
	s_add_i32 m0, s39, 0x2000
	v_lshl_add_u64 v[210:211], s[18:19], 0, v[158:159]
	global_load_lds_dwordx4 v[210:211], off
	s_mov_b32 m0, s29
	v_lshl_add_u64 v[210:211], s[16:17], 0, v[156:157]
	global_load_lds_dwordx4 v[210:211], off
	s_mov_b32 m0, s30
	v_lshl_add_u64 v[210:211], s[16:17], 0, v[158:159]
	global_load_lds_dwordx4 v[210:211], off
	s_add_u32 s14, s14, 0x84000
	s_addc_u32 s15, s15, 0
	s_add_i32 s16, s40, s23
	s_mov_b32 m0, s16
	v_lshl_add_u64 v[210:211], s[14:15], 0, v[156:157]
	global_load_lds_dwordx4 v[210:211], off
	s_add_i32 m0, s16, 0x2000
	v_lshl_add_u64 v[210:211], s[14:15], 0, v[158:159]
	global_load_lds_dwordx4 v[210:211], off
	ds_read_b128 v[144:147], v172 offset:49152
	ds_read_b128 v[166:169], v172 offset:51200
	ds_read_b128 v[178:181], v172 offset:53248
	ds_read_b128 v[186:189], v172 offset:55296
	ds_read_b128 v[148:151], v172 offset:50176
	ds_read_b128 v[174:177], v172 offset:52224
	ds_read_b128 v[182:185], v172 offset:54272
	ds_read_b128 v[190:193], v172 offset:56320
	s_waitcnt vmcnt(6)
	s_waitcnt lgkmcnt(0)
	s_barrier
	v_mfma_f32_16x16x32_bf16 v[60:63], v[128:131], v[144:147], v[60:63]
	s_setprio 1
	v_mfma_f32_16x16x32_bf16 v[56:59], v[136:139], v[144:147], v[56:59]
	v_mfma_f32_16x16x32_bf16 v[44:47], v[128:131], v[166:169], v[44:47]
	v_mfma_f32_16x16x32_bf16 v[40:43], v[136:139], v[166:169], v[40:43]
	v_mfma_f32_16x16x32_bf16 v[28:31], v[128:131], v[178:181], v[28:31]
	v_mfma_f32_16x16x32_bf16 v[24:27], v[136:139], v[178:181], v[24:27]
	v_mfma_f32_16x16x32_bf16 v[12:15], v[128:131], v[186:189], v[12:15]
	v_mfma_f32_16x16x32_bf16 v[8:11], v[136:139], v[186:189], v[8:11]
	v_mfma_f32_16x16x32_bf16 v[60:63], v[132:135], v[148:151], v[60:63]
	v_mfma_f32_16x16x32_bf16 v[56:59], v[140:143], v[148:151], v[56:59]
	v_mfma_f32_16x16x32_bf16 v[44:47], v[132:135], v[174:177], v[44:47]
	v_mfma_f32_16x16x32_bf16 v[40:43], v[140:143], v[174:177], v[40:43]
	v_mfma_f32_16x16x32_bf16 v[28:31], v[132:135], v[182:185], v[28:31]
	v_mfma_f32_16x16x32_bf16 v[24:27], v[140:143], v[182:185], v[24:27]
	v_mfma_f32_16x16x32_bf16 v[12:15], v[132:135], v[190:193], v[12:15]
	v_mfma_f32_16x16x32_bf16 v[8:11], v[140:143], v[190:193], v[8:11]
	v_mfma_f32_16x16x32_bf16 v[52:55], v[194:197], v[144:147], v[52:55]
	v_mfma_f32_16x16x32_bf16 v[48:51], v[202:205], v[144:147], v[48:51]
	s_add_i32 s38, s38, 2
	s_add_u32 s12, s12, 0x8000
	s_addc_u32 s13, s13, 0
	s_add_u32 s36, s36, 0x8000
	s_addc_u32 s37, s37, 0
	v_mfma_f32_16x16x32_bf16 v[36:39], v[194:197], v[166:169], v[36:39]
	v_mfma_f32_16x16x32_bf16 v[32:35], v[202:205], v[166:169], v[32:35]
	v_mfma_f32_16x16x32_bf16 v[20:23], v[194:197], v[178:181], v[20:23]
	v_mfma_f32_16x16x32_bf16 v[16:19], v[202:205], v[178:181], v[16:19]
	v_mfma_f32_16x16x32_bf16 v[4:7], v[194:197], v[186:189], v[4:7]
	v_mfma_f32_16x16x32_bf16 v[0:3], v[202:205], v[186:189], v[0:3]
	v_mfma_f32_16x16x32_bf16 v[52:55], v[198:201], v[148:151], v[52:55]
	v_mfma_f32_16x16x32_bf16 v[48:51], v[206:209], v[148:151], v[48:51]
	v_mfma_f32_16x16x32_bf16 v[36:39], v[198:201], v[174:177], v[36:39]
	v_mfma_f32_16x16x32_bf16 v[32:35], v[206:209], v[174:177], v[32:35]
	v_mfma_f32_16x16x32_bf16 v[20:23], v[198:201], v[182:185], v[20:23]
	v_mfma_f32_16x16x32_bf16 v[16:19], v[206:209], v[182:185], v[16:19]
	v_mfma_f32_16x16x32_bf16 v[4:7], v[198:201], v[190:193], v[4:7]
	s_cmp_gt_u32 s38, 29
	s_setprio 0
	v_mfma_f32_16x16x32_bf16 v[0:3], v[206:209], v[190:193], v[0:3]
	s_barrier
	s_cbranch_scc0 .LBB0_247
